# EpiResid epilogues: residual loads and bf16 stores both lane-permuted (coalesced 64-B row segments)
# baseline (speedup 1.0000x reference)
.LBB0_1016:
	v_mbcnt_lo_u32_b32 v252, -1, 0
	v_mbcnt_hi_u32_b32 v252, -1, v252
	v_and_b32_e32 v250, 3, v252
	v_lshrrev_b32_e32 v252, 2, v252
	v_lshl_or_b32 v252, v250, 4, v252
	v_lshlrev_b32_e32 v252, 2, v252
	v_lshl_add_u32 v238, s44, 8, v146
	v_and_b32_e32 v240, 0xe0, v148
	v_and_b32_e32 v241, 4, v148
	v_lshl_or_b32 v240, v241, 2, v240
	v_and_b32_e32 v241, 8, v148
	v_or_b32_e32 v240, v240, v241
	v_lshl_or_b32 v240, s45, 8, v240
	v_mov_b32_e32 v241, 0
	v_ashrrev_i32_e32 v239, 31, v238
	v_readlane_b32 s20, v234, 22
	v_readlane_b32 s21, v234, 23
	v_lshlrev_b64 v[244:245], 11, v[238:239]
	v_lshl_add_u64 v[244:245], v[244:245], 0, v[240:241]
	v_lshl_add_u64 v[144:145], v[244:245], 1, s[20:21]
	v_mbcnt_lo_u32_b32 v253, -1, 0
	v_mbcnt_hi_u32_b32 v253, -1, v253
	v_and_b32_e32 v254, 15, v253
	v_lshrrev_b32_e32 v253, 4, v253
	v_lshl_or_b32 v253, v254, 2, v253
	v_lshlrev_b32_e32 v253, 2, v253
	ds_bpermute_b32 v254, v252, v144
	ds_bpermute_b32 v255, v252, v145
	s_waitcnt lgkmcnt(0)
	s_mov_b32 s101, 0
	global_load_dwordx4 v[140:143], v[254:255], off
	global_load_dwordx4 v[154:157], v[254:255], off offset:256
	s_mov_b32 s100, 0x10000
	v_lshl_add_u64 v[236:237], v[254:255], 0, s[100:101]
	global_load_dwordx4 v[158:161], v[236:237], off
	global_load_dwordx4 v[162:165], v[236:237], off offset:256
	s_mov_b32 s100, 0x20000
	v_lshl_add_u64 v[236:237], v[254:255], 0, s[100:101]
	global_load_dwordx4 v[166:169], v[236:237], off
	global_load_dwordx4 v[170:173], v[236:237], off offset:256
	s_mov_b32 s100, 0x30000
	v_lshl_add_u64 v[236:237], v[254:255], 0, s[100:101]
	global_load_dwordx4 v[174:177], v[236:237], off
	global_load_dwordx4 v[178:181], v[236:237], off offset:256
	s_mov_b32 s100, 0x80000
	v_lshl_add_u64 v[236:237], v[254:255], 0, s[100:101]
	global_load_dwordx4 v[184:187], v[236:237], off
	global_load_dwordx4 v[190:193], v[236:237], off offset:256
	s_mov_b32 s100, 0x90000
	v_lshl_add_u64 v[236:237], v[254:255], 0, s[100:101]
	global_load_dwordx4 v[194:197], v[236:237], off
	global_load_dwordx4 v[198:201], v[236:237], off offset:256
	s_mov_b32 s100, 0xa0000
	v_lshl_add_u64 v[236:237], v[254:255], 0, s[100:101]
	global_load_dwordx4 v[202:205], v[236:237], off
	global_load_dwordx4 v[206:209], v[236:237], off offset:256
	s_mov_b32 s100, 0xb0000
	v_lshl_add_u64 v[236:237], v[254:255], 0, s[100:101]
	global_load_dwordx4 v[210:213], v[236:237], off
	global_load_dwordx4 v[214:217], v[236:237], off offset:256
	v_xor_b32_e32 v153, 16, v152
	v_xor_b32_e32 v242, 32, v152
	v_lshlrev_b32_e32 v153, 2, v153
	v_lshlrev_b32_e32 v242, 2, v242
	v_permlane16_swap_b32_e32 v124, v120
	v_permlane16_swap_b32_e32 v125, v121
	v_permlane16_swap_b32_e32 v126, v122
	v_permlane16_swap_b32_e32 v127, v123
	v_permlane16_swap_b32_e32 v116, v112
	v_permlane16_swap_b32_e32 v117, v113
	v_permlane16_swap_b32_e32 v118, v114
	v_permlane16_swap_b32_e32 v119, v115
	v_permlane16_swap_b32_e32 v108, v104
	v_permlane16_swap_b32_e32 v109, v105
	v_permlane16_swap_b32_e32 v110, v106
	v_permlane16_swap_b32_e32 v111, v107
	v_permlane16_swap_b32_e32 v100, v96
	v_permlane16_swap_b32_e32 v101, v97
	v_permlane16_swap_b32_e32 v102, v98
	v_permlane16_swap_b32_e32 v103, v99
	v_permlane16_swap_b32_e32 v92, v88
	v_permlane16_swap_b32_e32 v93, v89
	v_permlane16_swap_b32_e32 v94, v90
	v_permlane16_swap_b32_e32 v95, v91
	v_permlane16_swap_b32_e32 v84, v80
	v_permlane16_swap_b32_e32 v85, v81
	v_permlane16_swap_b32_e32 v86, v82
	v_permlane16_swap_b32_e32 v87, v83
	v_permlane16_swap_b32_e32 v76, v72
	v_permlane16_swap_b32_e32 v77, v73
	v_permlane16_swap_b32_e32 v78, v74
	v_permlane16_swap_b32_e32 v79, v75
	v_permlane16_swap_b32_e32 v68, v64
	v_permlane16_swap_b32_e32 v69, v65
	v_permlane16_swap_b32_e32 v70, v66
	v_permlane16_swap_b32_e32 v71, v67
	v_permlane16_swap_b32_e32 v60, v56
	v_permlane16_swap_b32_e32 v61, v57
	v_permlane16_swap_b32_e32 v62, v58
	v_permlane16_swap_b32_e32 v63, v59
	v_permlane16_swap_b32_e32 v52, v48
	v_permlane16_swap_b32_e32 v53, v49
	v_permlane16_swap_b32_e32 v54, v50
	v_permlane16_swap_b32_e32 v55, v51
	v_permlane16_swap_b32_e32 v44, v40
	v_permlane16_swap_b32_e32 v45, v41
	v_permlane16_swap_b32_e32 v46, v42
	v_permlane16_swap_b32_e32 v47, v43
	v_permlane16_swap_b32_e32 v36, v32
	v_permlane16_swap_b32_e32 v37, v33
	v_permlane16_swap_b32_e32 v38, v34
	v_permlane16_swap_b32_e32 v39, v35
	v_permlane16_swap_b32_e32 v28, v24
	v_permlane16_swap_b32_e32 v29, v25
	v_permlane16_swap_b32_e32 v30, v26
	v_permlane16_swap_b32_e32 v31, v27
	v_permlane16_swap_b32_e32 v20, v16
	v_permlane16_swap_b32_e32 v21, v17
	v_permlane16_swap_b32_e32 v22, v18
	v_permlane16_swap_b32_e32 v23, v19
	v_permlane16_swap_b32_e32 v12, v8
	v_permlane16_swap_b32_e32 v13, v9
	v_permlane16_swap_b32_e32 v14, v10
	v_permlane16_swap_b32_e32 v15, v11
	v_permlane16_swap_b32_e32 v4, v0
	v_permlane16_swap_b32_e32 v5, v1
	v_permlane16_swap_b32_e32 v6, v2
	v_permlane16_swap_b32_e32 v7, v3
	s_waitcnt vmcnt(14)
	ds_bpermute_b32 v140, v253, v140
	ds_bpermute_b32 v141, v253, v141
	ds_bpermute_b32 v142, v253, v142
	ds_bpermute_b32 v143, v253, v143
	ds_bpermute_b32 v154, v253, v154
	ds_bpermute_b32 v155, v253, v155
	ds_bpermute_b32 v156, v253, v156
	ds_bpermute_b32 v157, v253, v157
	s_waitcnt lgkmcnt(0)
	v_lshlrev_b32_e32 v244, 16, v140
	v_and_b32_e32 v245, 0xffff0000, v140
	v_fma_f32 v124, v124, 0.5, v244
	v_fma_f32 v125, v125, 0.5, v245
	v_mul_f32_e32 v243, v124, v124
	v_fmac_f32_e32 v243, v125, v125
	v_cvt_pk_bf16_f32 v140, v124, v125
	v_lshlrev_b32_e32 v244, 16, v141
	v_and_b32_e32 v245, 0xffff0000, v141
	v_fma_f32 v126, v126, 0.5, v244
	v_fma_f32 v127, v127, 0.5, v245
	v_fmac_f32_e32 v243, v126, v126
	v_fmac_f32_e32 v243, v127, v127
	v_cvt_pk_bf16_f32 v141, v126, v127
	v_lshlrev_b32_e32 v244, 16, v142
	v_and_b32_e32 v245, 0xffff0000, v142
	v_fma_f32 v120, v120, 0.5, v244
	v_fma_f32 v121, v121, 0.5, v245
	v_fmac_f32_e32 v243, v120, v120
	v_fmac_f32_e32 v243, v121, v121
	v_cvt_pk_bf16_f32 v142, v120, v121
	v_lshlrev_b32_e32 v244, 16, v143
	v_and_b32_e32 v245, 0xffff0000, v143
	v_fma_f32 v122, v122, 0.5, v244
	v_fma_f32 v123, v123, 0.5, v245
	v_fmac_f32_e32 v243, v122, v122
	v_fmac_f32_e32 v243, v123, v123
	v_cvt_pk_bf16_f32 v143, v122, v123
	ds_bpermute_b32 v250, v252, v144
	ds_bpermute_b32 v251, v252, v145
	ds_bpermute_b32 v140, v252, v140
	ds_bpermute_b32 v141, v252, v141
	ds_bpermute_b32 v142, v252, v142
	ds_bpermute_b32 v143, v252, v143
	s_waitcnt lgkmcnt(0)
	global_store_dwordx4 v[250:251], v[140:143], off
	v_lshlrev_b32_e32 v244, 16, v154
	v_and_b32_e32 v245, 0xffff0000, v154
	v_fma_f32 v116, v116, 0.5, v244
	v_fma_f32 v117, v117, 0.5, v245
	v_fmac_f32_e32 v243, v116, v116
	v_fmac_f32_e32 v243, v117, v117
	v_cvt_pk_bf16_f32 v154, v116, v117
	v_lshlrev_b32_e32 v244, 16, v155
	v_and_b32_e32 v245, 0xffff0000, v155
	v_fma_f32 v118, v118, 0.5, v244
	v_fma_f32 v119, v119, 0.5, v245
	v_fmac_f32_e32 v243, v118, v118
	v_fmac_f32_e32 v243, v119, v119
	v_cvt_pk_bf16_f32 v155, v118, v119
	v_lshlrev_b32_e32 v244, 16, v156
	v_and_b32_e32 v245, 0xffff0000, v156
	v_fma_f32 v112, v112, 0.5, v244
	v_fma_f32 v113, v113, 0.5, v245
	v_fmac_f32_e32 v243, v112, v112
	v_fmac_f32_e32 v243, v113, v113
	v_cvt_pk_bf16_f32 v156, v112, v113
	v_lshlrev_b32_e32 v244, 16, v157
	v_and_b32_e32 v245, 0xffff0000, v157
	v_fma_f32 v114, v114, 0.5, v244
	v_fma_f32 v115, v115, 0.5, v245
	v_fmac_f32_e32 v243, v114, v114
	v_fmac_f32_e32 v243, v115, v115
	v_cvt_pk_bf16_f32 v157, v114, v115
	ds_bpermute_b32 v154, v252, v154
	ds_bpermute_b32 v155, v252, v155
	ds_bpermute_b32 v156, v252, v156
	ds_bpermute_b32 v157, v252, v157
	s_waitcnt lgkmcnt(0)
	global_store_dwordx4 v[250:251], v[154:157], off offset:256
	s_waitcnt vmcnt(14)
	ds_bpermute_b32 v158, v253, v158
	ds_bpermute_b32 v159, v253, v159
	ds_bpermute_b32 v160, v253, v160
	ds_bpermute_b32 v161, v253, v161
	ds_bpermute_b32 v162, v253, v162
	ds_bpermute_b32 v163, v253, v163
	ds_bpermute_b32 v164, v253, v164
	ds_bpermute_b32 v165, v253, v165
	s_waitcnt lgkmcnt(0)
	s_mov_b32 s100, 0x10000
	v_lshl_add_u64 v[236:237], v[144:145], 0, s[100:101]
	v_lshlrev_b32_e32 v244, 16, v158
	v_and_b32_e32 v245, 0xffff0000, v158
	v_fma_f32 v108, v108, 0.5, v244
	v_fma_f32 v109, v109, 0.5, v245
	v_mul_f32_e32 v124, v108, v108
	v_fmac_f32_e32 v124, v109, v109
	v_cvt_pk_bf16_f32 v158, v108, v109
	v_lshlrev_b32_e32 v244, 16, v159
	v_and_b32_e32 v245, 0xffff0000, v159
	v_fma_f32 v110, v110, 0.5, v244
	v_fma_f32 v111, v111, 0.5, v245
	v_fmac_f32_e32 v124, v110, v110
	v_fmac_f32_e32 v124, v111, v111
	v_cvt_pk_bf16_f32 v159, v110, v111
	v_lshlrev_b32_e32 v244, 16, v160
	v_and_b32_e32 v245, 0xffff0000, v160
	v_fma_f32 v104, v104, 0.5, v244
	v_fma_f32 v105, v105, 0.5, v245
	v_fmac_f32_e32 v124, v104, v104
	v_fmac_f32_e32 v124, v105, v105
	v_cvt_pk_bf16_f32 v160, v104, v105
	v_lshlrev_b32_e32 v244, 16, v161
	v_and_b32_e32 v245, 0xffff0000, v161
	v_fma_f32 v106, v106, 0.5, v244
	v_fma_f32 v107, v107, 0.5, v245
	v_fmac_f32_e32 v124, v106, v106
	v_fmac_f32_e32 v124, v107, v107
	v_cvt_pk_bf16_f32 v161, v106, v107
	ds_bpermute_b32 v250, v252, v236
	ds_bpermute_b32 v251, v252, v237
	ds_bpermute_b32 v158, v252, v158
	ds_bpermute_b32 v159, v252, v159
	ds_bpermute_b32 v160, v252, v160
	ds_bpermute_b32 v161, v252, v161
	s_waitcnt lgkmcnt(0)
	global_store_dwordx4 v[250:251], v[158:161], off
	v_lshlrev_b32_e32 v244, 16, v162
	v_and_b32_e32 v245, 0xffff0000, v162
	v_fma_f32 v100, v100, 0.5, v244
	v_fma_f32 v101, v101, 0.5, v245
	v_fmac_f32_e32 v124, v100, v100
	v_fmac_f32_e32 v124, v101, v101
	v_cvt_pk_bf16_f32 v162, v100, v101
	v_lshlrev_b32_e32 v244, 16, v163
	v_and_b32_e32 v245, 0xffff0000, v163
	v_fma_f32 v102, v102, 0.5, v244
	v_fma_f32 v103, v103, 0.5, v245
	v_fmac_f32_e32 v124, v102, v102
	v_fmac_f32_e32 v124, v103, v103
	v_cvt_pk_bf16_f32 v163, v102, v103
	v_lshlrev_b32_e32 v244, 16, v164
	v_and_b32_e32 v245, 0xffff0000, v164
	v_fma_f32 v96, v96, 0.5, v244
	v_fma_f32 v97, v97, 0.5, v245
	v_fmac_f32_e32 v124, v96, v96
	v_fmac_f32_e32 v124, v97, v97
	v_cvt_pk_bf16_f32 v164, v96, v97
	v_lshlrev_b32_e32 v244, 16, v165
	v_and_b32_e32 v245, 0xffff0000, v165
	v_fma_f32 v98, v98, 0.5, v244
	v_fma_f32 v99, v99, 0.5, v245
	v_fmac_f32_e32 v124, v98, v98
	v_fmac_f32_e32 v124, v99, v99
	v_cvt_pk_bf16_f32 v165, v98, v99
	ds_bpermute_b32 v162, v252, v162
	ds_bpermute_b32 v163, v252, v163
	ds_bpermute_b32 v164, v252, v164
	ds_bpermute_b32 v165, v252, v165
	s_waitcnt lgkmcnt(0)
	global_store_dwordx4 v[250:251], v[162:165], off offset:256
	s_waitcnt vmcnt(14)
	ds_bpermute_b32 v166, v253, v166
	ds_bpermute_b32 v167, v253, v167
	ds_bpermute_b32 v168, v253, v168
	ds_bpermute_b32 v169, v253, v169
	ds_bpermute_b32 v170, v253, v170
	ds_bpermute_b32 v171, v253, v171
	ds_bpermute_b32 v172, v253, v172
	ds_bpermute_b32 v173, v253, v173
	s_waitcnt lgkmcnt(0)
	s_mov_b32 s100, 0x20000
	v_lshl_add_u64 v[236:237], v[144:145], 0, s[100:101]
	v_lshlrev_b32_e32 v244, 16, v166
	v_and_b32_e32 v245, 0xffff0000, v166
	v_fma_f32 v92, v92, 0.5, v244
	v_fma_f32 v93, v93, 0.5, v245
	v_mul_f32_e32 v108, v92, v92
	v_fmac_f32_e32 v108, v93, v93
	v_cvt_pk_bf16_f32 v166, v92, v93
	v_lshlrev_b32_e32 v244, 16, v167
	v_and_b32_e32 v245, 0xffff0000, v167
	v_fma_f32 v94, v94, 0.5, v244
	v_fma_f32 v95, v95, 0.5, v245
	v_fmac_f32_e32 v108, v94, v94
	v_fmac_f32_e32 v108, v95, v95
	v_cvt_pk_bf16_f32 v167, v94, v95
	v_lshlrev_b32_e32 v244, 16, v168
	v_and_b32_e32 v245, 0xffff0000, v168
	v_fma_f32 v88, v88, 0.5, v244
	v_fma_f32 v89, v89, 0.5, v245
	v_fmac_f32_e32 v108, v88, v88
	v_fmac_f32_e32 v108, v89, v89
	v_cvt_pk_bf16_f32 v168, v88, v89
	v_lshlrev_b32_e32 v244, 16, v169
	v_and_b32_e32 v245, 0xffff0000, v169
	v_fma_f32 v90, v90, 0.5, v244
	v_fma_f32 v91, v91, 0.5, v245
	v_fmac_f32_e32 v108, v90, v90
	v_fmac_f32_e32 v108, v91, v91
	v_cvt_pk_bf16_f32 v169, v90, v91
	ds_bpermute_b32 v250, v252, v236
	ds_bpermute_b32 v251, v252, v237
	ds_bpermute_b32 v166, v252, v166
	ds_bpermute_b32 v167, v252, v167
	ds_bpermute_b32 v168, v252, v168
	ds_bpermute_b32 v169, v252, v169
	s_waitcnt lgkmcnt(0)
	global_store_dwordx4 v[250:251], v[166:169], off
	v_lshlrev_b32_e32 v244, 16, v170
	v_and_b32_e32 v245, 0xffff0000, v170
	v_fma_f32 v84, v84, 0.5, v244
	v_fma_f32 v85, v85, 0.5, v245
	v_fmac_f32_e32 v108, v84, v84
	v_fmac_f32_e32 v108, v85, v85
	v_cvt_pk_bf16_f32 v170, v84, v85
	v_lshlrev_b32_e32 v244, 16, v171
	v_and_b32_e32 v245, 0xffff0000, v171
	v_fma_f32 v86, v86, 0.5, v244
	v_fma_f32 v87, v87, 0.5, v245
	v_fmac_f32_e32 v108, v86, v86
	v_fmac_f32_e32 v108, v87, v87
	v_cvt_pk_bf16_f32 v171, v86, v87
	v_lshlrev_b32_e32 v244, 16, v172
	v_and_b32_e32 v245, 0xffff0000, v172
	v_fma_f32 v80, v80, 0.5, v244
	v_fma_f32 v81, v81, 0.5, v245
	v_fmac_f32_e32 v108, v80, v80
	v_fmac_f32_e32 v108, v81, v81
	v_cvt_pk_bf16_f32 v172, v80, v81
	v_lshlrev_b32_e32 v244, 16, v173
	v_and_b32_e32 v245, 0xffff0000, v173
	v_fma_f32 v82, v82, 0.5, v244
	v_fma_f32 v83, v83, 0.5, v245
	v_fmac_f32_e32 v108, v82, v82
	v_fmac_f32_e32 v108, v83, v83
	v_cvt_pk_bf16_f32 v173, v82, v83
	ds_bpermute_b32 v170, v252, v170
	ds_bpermute_b32 v171, v252, v171
	ds_bpermute_b32 v172, v252, v172
	ds_bpermute_b32 v173, v252, v173
	s_waitcnt lgkmcnt(0)
	global_store_dwordx4 v[250:251], v[170:173], off offset:256
	s_waitcnt vmcnt(14)
	ds_bpermute_b32 v174, v253, v174
	ds_bpermute_b32 v175, v253, v175
	ds_bpermute_b32 v176, v253, v176
	ds_bpermute_b32 v177, v253, v177
	ds_bpermute_b32 v178, v253, v178
	ds_bpermute_b32 v179, v253, v179
	ds_bpermute_b32 v180, v253, v180
	ds_bpermute_b32 v181, v253, v181
	s_waitcnt lgkmcnt(0)
	s_mov_b32 s100, 0x30000
	v_lshl_add_u64 v[236:237], v[144:145], 0, s[100:101]
	v_lshlrev_b32_e32 v244, 16, v174
	v_and_b32_e32 v245, 0xffff0000, v174
	v_fma_f32 v76, v76, 0.5, v244
	v_fma_f32 v77, v77, 0.5, v245
	v_mul_f32_e32 v92, v76, v76
	v_fmac_f32_e32 v92, v77, v77
	v_cvt_pk_bf16_f32 v174, v76, v77
	v_lshlrev_b32_e32 v244, 16, v175
	v_and_b32_e32 v245, 0xffff0000, v175
	v_fma_f32 v78, v78, 0.5, v244
	v_fma_f32 v79, v79, 0.5, v245
	v_fmac_f32_e32 v92, v78, v78
	v_fmac_f32_e32 v92, v79, v79
	v_cvt_pk_bf16_f32 v175, v78, v79
	v_lshlrev_b32_e32 v244, 16, v176
	v_and_b32_e32 v245, 0xffff0000, v176
	v_fma_f32 v72, v72, 0.5, v244
	v_fma_f32 v73, v73, 0.5, v245
	v_fmac_f32_e32 v92, v72, v72
	v_fmac_f32_e32 v92, v73, v73
	v_cvt_pk_bf16_f32 v176, v72, v73
	v_lshlrev_b32_e32 v244, 16, v177
	v_and_b32_e32 v245, 0xffff0000, v177
	v_fma_f32 v74, v74, 0.5, v244
	v_fma_f32 v75, v75, 0.5, v245
	v_fmac_f32_e32 v92, v74, v74
	v_fmac_f32_e32 v92, v75, v75
	v_cvt_pk_bf16_f32 v177, v74, v75
	ds_bpermute_b32 v250, v252, v236
	ds_bpermute_b32 v251, v252, v237
	ds_bpermute_b32 v174, v252, v174
	ds_bpermute_b32 v175, v252, v175
	ds_bpermute_b32 v176, v252, v176
	ds_bpermute_b32 v177, v252, v177
	s_waitcnt lgkmcnt(0)
	global_store_dwordx4 v[250:251], v[174:177], off
	v_lshlrev_b32_e32 v244, 16, v178
	v_and_b32_e32 v245, 0xffff0000, v178
	v_fma_f32 v68, v68, 0.5, v244
	v_fma_f32 v69, v69, 0.5, v245
	v_fmac_f32_e32 v92, v68, v68
	v_fmac_f32_e32 v92, v69, v69
	v_cvt_pk_bf16_f32 v178, v68, v69
	v_lshlrev_b32_e32 v244, 16, v179
	v_and_b32_e32 v245, 0xffff0000, v179
	v_fma_f32 v70, v70, 0.5, v244
	v_fma_f32 v71, v71, 0.5, v245
	v_fmac_f32_e32 v92, v70, v70
	v_fmac_f32_e32 v92, v71, v71
	v_cvt_pk_bf16_f32 v179, v70, v71
	v_lshlrev_b32_e32 v244, 16, v180
	v_and_b32_e32 v245, 0xffff0000, v180
	v_fma_f32 v64, v64, 0.5, v244
	v_fma_f32 v65, v65, 0.5, v245
	v_fmac_f32_e32 v92, v64, v64
	v_fmac_f32_e32 v92, v65, v65
	v_cvt_pk_bf16_f32 v180, v64, v65
	v_lshlrev_b32_e32 v244, 16, v181
	v_and_b32_e32 v245, 0xffff0000, v181
	v_fma_f32 v66, v66, 0.5, v244
	v_fma_f32 v67, v67, 0.5, v245
	v_fmac_f32_e32 v92, v66, v66
	v_fmac_f32_e32 v92, v67, v67
	v_cvt_pk_bf16_f32 v181, v66, v67
	ds_bpermute_b32 v178, v252, v178
	ds_bpermute_b32 v179, v252, v179
	ds_bpermute_b32 v180, v252, v180
	ds_bpermute_b32 v181, v252, v181
	s_waitcnt lgkmcnt(0)
	global_store_dwordx4 v[250:251], v[178:181], off offset:256
	s_waitcnt vmcnt(14)
	ds_bpermute_b32 v184, v253, v184
	ds_bpermute_b32 v185, v253, v185
	ds_bpermute_b32 v186, v253, v186
	ds_bpermute_b32 v187, v253, v187
	ds_bpermute_b32 v190, v253, v190
	ds_bpermute_b32 v191, v253, v191
	ds_bpermute_b32 v192, v253, v192
	ds_bpermute_b32 v193, v253, v193
	s_waitcnt lgkmcnt(0)
	s_mov_b32 s100, 0x80000
	v_lshl_add_u64 v[236:237], v[144:145], 0, s[100:101]
	v_lshlrev_b32_e32 v244, 16, v184
	v_and_b32_e32 v245, 0xffff0000, v184
	v_fma_f32 v60, v60, 0.5, v244
	v_fma_f32 v61, v61, 0.5, v245
	v_mul_f32_e32 v76, v60, v60
	v_fmac_f32_e32 v76, v61, v61
	v_cvt_pk_bf16_f32 v184, v60, v61
	v_lshlrev_b32_e32 v244, 16, v185
	v_and_b32_e32 v245, 0xffff0000, v185
	v_fma_f32 v62, v62, 0.5, v244
	v_fma_f32 v63, v63, 0.5, v245
	v_fmac_f32_e32 v76, v62, v62
	v_fmac_f32_e32 v76, v63, v63
	v_cvt_pk_bf16_f32 v185, v62, v63
	v_lshlrev_b32_e32 v244, 16, v186
	v_and_b32_e32 v245, 0xffff0000, v186
	v_fma_f32 v56, v56, 0.5, v244
	v_fma_f32 v57, v57, 0.5, v245
	v_fmac_f32_e32 v76, v56, v56
	v_fmac_f32_e32 v76, v57, v57
	v_cvt_pk_bf16_f32 v186, v56, v57
	v_lshlrev_b32_e32 v244, 16, v187
	v_and_b32_e32 v245, 0xffff0000, v187
	v_fma_f32 v58, v58, 0.5, v244
	v_fma_f32 v59, v59, 0.5, v245
	v_fmac_f32_e32 v76, v58, v58
	v_fmac_f32_e32 v76, v59, v59
	v_cvt_pk_bf16_f32 v187, v58, v59
	ds_bpermute_b32 v250, v252, v236
	ds_bpermute_b32 v251, v252, v237
	ds_bpermute_b32 v184, v252, v184
	ds_bpermute_b32 v185, v252, v185
	ds_bpermute_b32 v186, v252, v186
	ds_bpermute_b32 v187, v252, v187
	s_waitcnt lgkmcnt(0)
	global_store_dwordx4 v[250:251], v[184:187], off
	v_lshlrev_b32_e32 v244, 16, v190
	v_and_b32_e32 v245, 0xffff0000, v190
	v_fma_f32 v52, v52, 0.5, v244
	v_fma_f32 v53, v53, 0.5, v245
	v_fmac_f32_e32 v76, v52, v52
	v_fmac_f32_e32 v76, v53, v53
	v_cvt_pk_bf16_f32 v190, v52, v53
	v_lshlrev_b32_e32 v244, 16, v191
	v_and_b32_e32 v245, 0xffff0000, v191
	v_fma_f32 v54, v54, 0.5, v244
	v_fma_f32 v55, v55, 0.5, v245
	v_fmac_f32_e32 v76, v54, v54
	v_fmac_f32_e32 v76, v55, v55
	v_cvt_pk_bf16_f32 v191, v54, v55
	v_lshlrev_b32_e32 v244, 16, v192
	v_and_b32_e32 v245, 0xffff0000, v192
	v_fma_f32 v48, v48, 0.5, v244
	v_fma_f32 v49, v49, 0.5, v245
	v_fmac_f32_e32 v76, v48, v48
	v_fmac_f32_e32 v76, v49, v49
	v_cvt_pk_bf16_f32 v192, v48, v49
	v_lshlrev_b32_e32 v244, 16, v193
	v_and_b32_e32 v245, 0xffff0000, v193
	v_fma_f32 v50, v50, 0.5, v244
	v_fma_f32 v51, v51, 0.5, v245
	v_fmac_f32_e32 v76, v50, v50
	v_fmac_f32_e32 v76, v51, v51
	v_cvt_pk_bf16_f32 v193, v50, v51
	ds_bpermute_b32 v190, v252, v190
	ds_bpermute_b32 v191, v252, v191
	ds_bpermute_b32 v192, v252, v192
	ds_bpermute_b32 v193, v252, v193
	s_waitcnt lgkmcnt(0)
	global_store_dwordx4 v[250:251], v[190:193], off offset:256
	s_waitcnt vmcnt(14)
	ds_bpermute_b32 v194, v253, v194
	ds_bpermute_b32 v195, v253, v195
	ds_bpermute_b32 v196, v253, v196
	ds_bpermute_b32 v197, v253, v197
	ds_bpermute_b32 v198, v253, v198
	ds_bpermute_b32 v199, v253, v199
	ds_bpermute_b32 v200, v253, v200
	ds_bpermute_b32 v201, v253, v201
	s_waitcnt lgkmcnt(0)
	s_mov_b32 s100, 0x90000
	v_lshl_add_u64 v[236:237], v[144:145], 0, s[100:101]
	v_lshlrev_b32_e32 v244, 16, v194
	v_and_b32_e32 v245, 0xffff0000, v194
	v_fma_f32 v44, v44, 0.5, v244
	v_fma_f32 v45, v45, 0.5, v245
	v_mul_f32_e32 v60, v44, v44
	v_fmac_f32_e32 v60, v45, v45
	v_cvt_pk_bf16_f32 v194, v44, v45
	v_lshlrev_b32_e32 v244, 16, v195
	v_and_b32_e32 v245, 0xffff0000, v195
	v_fma_f32 v46, v46, 0.5, v244
	v_fma_f32 v47, v47, 0.5, v245
	v_fmac_f32_e32 v60, v46, v46
	v_fmac_f32_e32 v60, v47, v47
	v_cvt_pk_bf16_f32 v195, v46, v47
	v_lshlrev_b32_e32 v244, 16, v196
	v_and_b32_e32 v245, 0xffff0000, v196
	v_fma_f32 v40, v40, 0.5, v244
	v_fma_f32 v41, v41, 0.5, v245
	v_fmac_f32_e32 v60, v40, v40
	v_fmac_f32_e32 v60, v41, v41
	v_cvt_pk_bf16_f32 v196, v40, v41
	v_lshlrev_b32_e32 v244, 16, v197
	v_and_b32_e32 v245, 0xffff0000, v197
	v_fma_f32 v42, v42, 0.5, v244
	v_fma_f32 v43, v43, 0.5, v245
	v_fmac_f32_e32 v60, v42, v42
	v_fmac_f32_e32 v60, v43, v43
	v_cvt_pk_bf16_f32 v197, v42, v43
	ds_bpermute_b32 v250, v252, v236
	ds_bpermute_b32 v251, v252, v237
	ds_bpermute_b32 v194, v252, v194
	ds_bpermute_b32 v195, v252, v195
	ds_bpermute_b32 v196, v252, v196
	ds_bpermute_b32 v197, v252, v197
	s_waitcnt lgkmcnt(0)
	global_store_dwordx4 v[250:251], v[194:197], off
	v_lshlrev_b32_e32 v244, 16, v198
	v_and_b32_e32 v245, 0xffff0000, v198
	v_fma_f32 v36, v36, 0.5, v244
	v_fma_f32 v37, v37, 0.5, v245
	v_fmac_f32_e32 v60, v36, v36
	v_fmac_f32_e32 v60, v37, v37
	v_cvt_pk_bf16_f32 v198, v36, v37
	v_lshlrev_b32_e32 v244, 16, v199
	v_and_b32_e32 v245, 0xffff0000, v199
	v_fma_f32 v38, v38, 0.5, v244
	v_fma_f32 v39, v39, 0.5, v245
	v_fmac_f32_e32 v60, v38, v38
	v_fmac_f32_e32 v60, v39, v39
	v_cvt_pk_bf16_f32 v199, v38, v39
	v_lshlrev_b32_e32 v244, 16, v200
	v_and_b32_e32 v245, 0xffff0000, v200
	v_fma_f32 v32, v32, 0.5, v244
	v_fma_f32 v33, v33, 0.5, v245
	v_fmac_f32_e32 v60, v32, v32
	v_fmac_f32_e32 v60, v33, v33
	v_cvt_pk_bf16_f32 v200, v32, v33
	v_lshlrev_b32_e32 v244, 16, v201
	v_and_b32_e32 v245, 0xffff0000, v201
	v_fma_f32 v34, v34, 0.5, v244
	v_fma_f32 v35, v35, 0.5, v245
	v_fmac_f32_e32 v60, v34, v34
	v_fmac_f32_e32 v60, v35, v35
	v_cvt_pk_bf16_f32 v201, v34, v35
	ds_bpermute_b32 v198, v252, v198
	ds_bpermute_b32 v199, v252, v199
	ds_bpermute_b32 v200, v252, v200
	ds_bpermute_b32 v201, v252, v201
	s_waitcnt lgkmcnt(0)
	global_store_dwordx4 v[250:251], v[198:201], off offset:256
	s_waitcnt vmcnt(14)
	ds_bpermute_b32 v202, v253, v202
	ds_bpermute_b32 v203, v253, v203
	ds_bpermute_b32 v204, v253, v204
	ds_bpermute_b32 v205, v253, v205
	ds_bpermute_b32 v206, v253, v206
	ds_bpermute_b32 v207, v253, v207
	ds_bpermute_b32 v208, v253, v208
	ds_bpermute_b32 v209, v253, v209
	s_waitcnt lgkmcnt(0)
	s_mov_b32 s100, 0xa0000
	v_lshl_add_u64 v[236:237], v[144:145], 0, s[100:101]
	v_lshlrev_b32_e32 v244, 16, v202
	v_and_b32_e32 v245, 0xffff0000, v202
	v_fma_f32 v28, v28, 0.5, v244
	v_fma_f32 v29, v29, 0.5, v245
	v_mul_f32_e32 v44, v28, v28
	v_fmac_f32_e32 v44, v29, v29
	v_cvt_pk_bf16_f32 v202, v28, v29
	v_lshlrev_b32_e32 v244, 16, v203
	v_and_b32_e32 v245, 0xffff0000, v203
	v_fma_f32 v30, v30, 0.5, v244
	v_fma_f32 v31, v31, 0.5, v245
	v_fmac_f32_e32 v44, v30, v30
	v_fmac_f32_e32 v44, v31, v31
	v_cvt_pk_bf16_f32 v203, v30, v31
	v_lshlrev_b32_e32 v244, 16, v204
	v_and_b32_e32 v245, 0xffff0000, v204
	v_fma_f32 v24, v24, 0.5, v244
	v_fma_f32 v25, v25, 0.5, v245
	v_fmac_f32_e32 v44, v24, v24
	v_fmac_f32_e32 v44, v25, v25
	v_cvt_pk_bf16_f32 v204, v24, v25
	v_lshlrev_b32_e32 v244, 16, v205
	v_and_b32_e32 v245, 0xffff0000, v205
	v_fma_f32 v26, v26, 0.5, v244
	v_fma_f32 v27, v27, 0.5, v245
	v_fmac_f32_e32 v44, v26, v26
	v_fmac_f32_e32 v44, v27, v27
	v_cvt_pk_bf16_f32 v205, v26, v27
	ds_bpermute_b32 v250, v252, v236
	ds_bpermute_b32 v251, v252, v237
	ds_bpermute_b32 v202, v252, v202
	ds_bpermute_b32 v203, v252, v203
	ds_bpermute_b32 v204, v252, v204
	ds_bpermute_b32 v205, v252, v205
	s_waitcnt lgkmcnt(0)
	global_store_dwordx4 v[250:251], v[202:205], off
	v_lshlrev_b32_e32 v244, 16, v206
	v_and_b32_e32 v245, 0xffff0000, v206
	v_fma_f32 v20, v20, 0.5, v244
	v_fma_f32 v21, v21, 0.5, v245
	v_fmac_f32_e32 v44, v20, v20
	v_fmac_f32_e32 v44, v21, v21
	v_cvt_pk_bf16_f32 v206, v20, v21
	v_lshlrev_b32_e32 v244, 16, v207
	v_and_b32_e32 v245, 0xffff0000, v207
	v_fma_f32 v22, v22, 0.5, v244
	v_fma_f32 v23, v23, 0.5, v245
	v_fmac_f32_e32 v44, v22, v22
	v_fmac_f32_e32 v44, v23, v23
	v_cvt_pk_bf16_f32 v207, v22, v23
	v_lshlrev_b32_e32 v244, 16, v208
	v_and_b32_e32 v245, 0xffff0000, v208
	v_fma_f32 v16, v16, 0.5, v244
	v_fma_f32 v17, v17, 0.5, v245
	v_fmac_f32_e32 v44, v16, v16
	v_fmac_f32_e32 v44, v17, v17
	v_cvt_pk_bf16_f32 v208, v16, v17
	v_lshlrev_b32_e32 v244, 16, v209
	v_and_b32_e32 v245, 0xffff0000, v209
	v_fma_f32 v18, v18, 0.5, v244
	v_fma_f32 v19, v19, 0.5, v245
	v_fmac_f32_e32 v44, v18, v18
	v_fmac_f32_e32 v44, v19, v19
	v_cvt_pk_bf16_f32 v209, v18, v19
	ds_bpermute_b32 v206, v252, v206
	ds_bpermute_b32 v207, v252, v207
	ds_bpermute_b32 v208, v252, v208
	ds_bpermute_b32 v209, v252, v209
	s_waitcnt lgkmcnt(0)
	global_store_dwordx4 v[250:251], v[206:209], off offset:256
	s_waitcnt vmcnt(14)
	ds_bpermute_b32 v210, v253, v210
	ds_bpermute_b32 v211, v253, v211
	ds_bpermute_b32 v212, v253, v212
	ds_bpermute_b32 v213, v253, v213
	ds_bpermute_b32 v214, v253, v214
	ds_bpermute_b32 v215, v253, v215
	ds_bpermute_b32 v216, v253, v216
	ds_bpermute_b32 v217, v253, v217
	s_waitcnt lgkmcnt(0)
	s_mov_b32 s100, 0xb0000
	v_lshl_add_u64 v[236:237], v[144:145], 0, s[100:101]
	v_lshlrev_b32_e32 v244, 16, v210
	v_and_b32_e32 v245, 0xffff0000, v210
	v_fma_f32 v12, v12, 0.5, v244
	v_fma_f32 v13, v13, 0.5, v245
	v_mul_f32_e32 v28, v12, v12
	v_fmac_f32_e32 v28, v13, v13
	v_cvt_pk_bf16_f32 v210, v12, v13
	v_lshlrev_b32_e32 v244, 16, v211
	v_and_b32_e32 v245, 0xffff0000, v211
	v_fma_f32 v14, v14, 0.5, v244
	v_fma_f32 v15, v15, 0.5, v245
	v_fmac_f32_e32 v28, v14, v14
	v_fmac_f32_e32 v28, v15, v15
	v_cvt_pk_bf16_f32 v211, v14, v15
	v_lshlrev_b32_e32 v244, 16, v212
	v_and_b32_e32 v245, 0xffff0000, v212
	v_fma_f32 v8, v8, 0.5, v244
	v_fma_f32 v9, v9, 0.5, v245
	v_fmac_f32_e32 v28, v8, v8
	v_fmac_f32_e32 v28, v9, v9
	v_cvt_pk_bf16_f32 v212, v8, v9
	v_lshlrev_b32_e32 v244, 16, v213
	v_and_b32_e32 v245, 0xffff0000, v213
	v_fma_f32 v10, v10, 0.5, v244
	v_fma_f32 v11, v11, 0.5, v245
	v_fmac_f32_e32 v28, v10, v10
	v_fmac_f32_e32 v28, v11, v11
	v_cvt_pk_bf16_f32 v213, v10, v11
	ds_bpermute_b32 v250, v252, v236
	ds_bpermute_b32 v251, v252, v237
	ds_bpermute_b32 v210, v252, v210
	ds_bpermute_b32 v211, v252, v211
	ds_bpermute_b32 v212, v252, v212
	ds_bpermute_b32 v213, v252, v213
	s_waitcnt lgkmcnt(0)
	global_store_dwordx4 v[250:251], v[210:213], off
	v_lshlrev_b32_e32 v244, 16, v214
	v_and_b32_e32 v245, 0xffff0000, v214
	v_fma_f32 v4, v4, 0.5, v244
	v_fma_f32 v5, v5, 0.5, v245
	v_fmac_f32_e32 v28, v4, v4
	v_fmac_f32_e32 v28, v5, v5
	v_cvt_pk_bf16_f32 v214, v4, v5
	v_lshlrev_b32_e32 v244, 16, v215
	v_and_b32_e32 v245, 0xffff0000, v215
	v_fma_f32 v6, v6, 0.5, v244
	v_fma_f32 v7, v7, 0.5, v245
	v_fmac_f32_e32 v28, v6, v6
	v_fmac_f32_e32 v28, v7, v7
	v_cvt_pk_bf16_f32 v215, v6, v7
	v_lshlrev_b32_e32 v244, 16, v216
	v_and_b32_e32 v245, 0xffff0000, v216
	v_fma_f32 v0, v0, 0.5, v244
	v_fma_f32 v1, v1, 0.5, v245
	v_fmac_f32_e32 v28, v0, v0
	v_fmac_f32_e32 v28, v1, v1
	v_cvt_pk_bf16_f32 v216, v0, v1
	v_lshlrev_b32_e32 v244, 16, v217
	v_and_b32_e32 v245, 0xffff0000, v217
	v_fma_f32 v2, v2, 0.5, v244
	v_fma_f32 v3, v3, 0.5, v245
	v_fmac_f32_e32 v28, v2, v2
	v_fmac_f32_e32 v28, v3, v3
	v_cvt_pk_bf16_f32 v217, v2, v3
	ds_bpermute_b32 v214, v252, v214
	ds_bpermute_b32 v215, v252, v215
	ds_bpermute_b32 v216, v252, v216
	ds_bpermute_b32 v217, v252, v217
	s_waitcnt lgkmcnt(0)
	global_store_dwordx4 v[250:251], v[214:217], off offset:256
	ds_bpermute_b32 v0, v153, v243
	ds_bpermute_b32 v1, v153, v124
	ds_bpermute_b32 v2, v153, v108
	ds_bpermute_b32 v3, v153, v92
	ds_bpermute_b32 v8, v153, v76
	ds_bpermute_b32 v9, v153, v60
	ds_bpermute_b32 v10, v153, v44
	ds_bpermute_b32 v11, v153, v28
	s_waitcnt lgkmcnt(7)
	v_add_f32_e32 v243, v243, v0
	s_waitcnt lgkmcnt(6)
	v_add_f32_e32 v124, v124, v1
	s_waitcnt lgkmcnt(5)
	v_add_f32_e32 v108, v108, v2
	s_waitcnt lgkmcnt(4)
	v_add_f32_e32 v92, v92, v3
	s_waitcnt lgkmcnt(3)
	v_add_f32_e32 v76, v76, v8
	s_waitcnt lgkmcnt(2)
	v_add_f32_e32 v60, v60, v9
	s_waitcnt lgkmcnt(1)
	v_add_f32_e32 v44, v44, v10
	s_waitcnt lgkmcnt(0)
	v_add_f32_e32 v28, v28, v11
	ds_bpermute_b32 v0, v242, v243
	ds_bpermute_b32 v1, v242, v124
	ds_bpermute_b32 v2, v242, v108
	ds_bpermute_b32 v3, v242, v92
	ds_bpermute_b32 v8, v242, v76
	ds_bpermute_b32 v9, v242, v60
	ds_bpermute_b32 v10, v242, v44
	ds_bpermute_b32 v11, v242, v28
	s_waitcnt lgkmcnt(7)
	v_add_f32_e32 v243, v243, v0
	s_waitcnt lgkmcnt(6)
	v_add_f32_e32 v124, v124, v1
	s_waitcnt lgkmcnt(5)
	v_add_f32_e32 v108, v108, v2
	s_waitcnt lgkmcnt(4)
	v_add_f32_e32 v92, v92, v3
	s_waitcnt lgkmcnt(3)
	v_add_f32_e32 v76, v76, v8
	s_waitcnt lgkmcnt(2)
	v_add_f32_e32 v60, v60, v9
	s_waitcnt lgkmcnt(1)
	v_add_f32_e32 v44, v44, v10
	s_waitcnt lgkmcnt(0)
	v_add_f32_e32 v28, v28, v11
	s_and_saveexec_b64 s[20:21], s[4:5]
	v_lshl_add_u64 v[144:145], v[238:239], 3, s[16:17]
	v_mul_f32_e32 v243, 0x4f800000, v243
	v_trunc_f32_e32 v243, v243
	v_mul_f32_e32 v0, 0x2f800000, v243
	v_floor_f32_e32 v0, v0
	v_fmac_f32_e32 v243, 0xcf800000, v0
	v_cvt_u32_f32_e32 v244, v243
	v_cvt_u32_f32_e32 v245, v0
	global_atomic_add_x2 v[144:145], v[244:245], off
	s_nop 1
	v_mul_f32_e32 v124, 0x4f800000, v124
	v_trunc_f32_e32 v124, v124
	v_mul_f32_e32 v1, 0x2f800000, v124
	v_floor_f32_e32 v1, v1
	v_fmac_f32_e32 v124, 0xcf800000, v1
	v_cvt_u32_f32_e32 v244, v124
	v_cvt_u32_f32_e32 v245, v1
	global_atomic_add_x2 v[144:145], v[244:245], off offset:128
	s_nop 1
	v_mul_f32_e32 v108, 0x4f800000, v108
	v_trunc_f32_e32 v108, v108
	v_mul_f32_e32 v2, 0x2f800000, v108
	v_floor_f32_e32 v2, v2
	v_fmac_f32_e32 v108, 0xcf800000, v2
	v_cvt_u32_f32_e32 v244, v108
	v_cvt_u32_f32_e32 v245, v2
	global_atomic_add_x2 v[144:145], v[244:245], off offset:256
	s_nop 1
	v_mul_f32_e32 v92, 0x4f800000, v92
	v_trunc_f32_e32 v92, v92
	v_mul_f32_e32 v3, 0x2f800000, v92
	v_floor_f32_e32 v3, v3
	v_fmac_f32_e32 v92, 0xcf800000, v3
	v_cvt_u32_f32_e32 v244, v92
	v_cvt_u32_f32_e32 v245, v3
	global_atomic_add_x2 v[144:145], v[244:245], off offset:384
	s_nop 1
	v_mul_f32_e32 v76, 0x4f800000, v76
	v_trunc_f32_e32 v76, v76
	v_mul_f32_e32 v8, 0x2f800000, v76
	v_floor_f32_e32 v8, v8
	v_fmac_f32_e32 v76, 0xcf800000, v8
	v_cvt_u32_f32_e32 v244, v76
	v_cvt_u32_f32_e32 v245, v8
	global_atomic_add_x2 v[144:145], v[244:245], off offset:1024
	s_nop 1
	v_mul_f32_e32 v60, 0x4f800000, v60
	v_trunc_f32_e32 v60, v60
	v_mul_f32_e32 v9, 0x2f800000, v60
	v_floor_f32_e32 v9, v9
	v_fmac_f32_e32 v60, 0xcf800000, v9
	v_cvt_u32_f32_e32 v244, v60
	v_cvt_u32_f32_e32 v245, v9
	global_atomic_add_x2 v[144:145], v[244:245], off offset:1152
	s_nop 1
	v_mul_f32_e32 v44, 0x4f800000, v44
	v_trunc_f32_e32 v44, v44
	v_mul_f32_e32 v10, 0x2f800000, v44
	v_floor_f32_e32 v10, v10
	v_fmac_f32_e32 v44, 0xcf800000, v10
	v_cvt_u32_f32_e32 v244, v44
	v_cvt_u32_f32_e32 v245, v10
	global_atomic_add_x2 v[144:145], v[244:245], off offset:1280
	s_nop 1
	v_mul_f32_e32 v28, 0x4f800000, v28
	v_trunc_f32_e32 v28, v28
	v_mul_f32_e32 v11, 0x2f800000, v28
	v_floor_f32_e32 v11, v11
	v_fmac_f32_e32 v28, 0xcf800000, v11
	v_cvt_u32_f32_e32 v244, v28
	v_cvt_u32_f32_e32 v245, v11
	global_atomic_add_x2 v[144:145], v[244:245], off offset:1408
	s_nop 1

.LBB0_2215:
	v_mbcnt_lo_u32_b32 v252, -1, 0
	v_mbcnt_hi_u32_b32 v252, -1, v252
	v_and_b32_e32 v250, 3, v252
	v_lshrrev_b32_e32 v252, 2, v252
	v_lshl_or_b32 v252, v250, 4, v252
	v_lshlrev_b32_e32 v252, 2, v252
	s_mov_b32 s52, s56
	v_lshl_add_u32 v240, s24, 8, v144
	v_and_b32_e32 v242, 0xe0, v146
	v_and_b32_e32 v243, 4, v146
	v_lshl_or_b32 v242, v243, 2, v242
	v_and_b32_e32 v243, 8, v146
	v_or_b32_e32 v242, v242, v243
	v_lshl_or_b32 v242, s26, 8, v242
	v_mov_b32_e32 v243, 0
	v_ashrrev_i32_e32 v241, 31, v240
	v_readlane_b32 s24, v234, 22
	v_readlane_b32 s25, v234, 23
	v_lshlrev_b64 v[246:247], 11, v[240:241]
	v_lshl_add_u64 v[246:247], v[246:247], 0, v[242:243]
	v_lshl_add_u64 v[236:237], v[246:247], 1, s[24:25]
	v_mbcnt_lo_u32_b32 v253, -1, 0
	v_mbcnt_hi_u32_b32 v253, -1, v253
	v_and_b32_e32 v254, 15, v253
	v_lshrrev_b32_e32 v253, 4, v253
	v_lshl_or_b32 v253, v254, 2, v253
	v_lshlrev_b32_e32 v253, 2, v253
	ds_bpermute_b32 v254, v252, v236
	ds_bpermute_b32 v255, v252, v237
	s_waitcnt lgkmcnt(0)
	s_mov_b32 s101, 0
	global_load_dwordx4 v[140:143], v[254:255], off
	global_load_dwordx4 v[154:157], v[254:255], off offset:256
	s_mov_b32 s100, 0x10000
	v_lshl_add_u64 v[238:239], v[254:255], 0, s[100:101]
	global_load_dwordx4 v[158:161], v[238:239], off
	global_load_dwordx4 v[162:165], v[238:239], off offset:256
	s_mov_b32 s100, 0x20000
	v_lshl_add_u64 v[238:239], v[254:255], 0, s[100:101]
	global_load_dwordx4 v[166:169], v[238:239], off
	global_load_dwordx4 v[170:173], v[238:239], off offset:256
	s_mov_b32 s100, 0x30000
	v_lshl_add_u64 v[238:239], v[254:255], 0, s[100:101]
	global_load_dwordx4 v[174:177], v[238:239], off
	global_load_dwordx4 v[178:181], v[238:239], off offset:256
	s_mov_b32 s100, 0x80000
	v_lshl_add_u64 v[238:239], v[254:255], 0, s[100:101]
	global_load_dwordx4 v[184:187], v[238:239], off
	global_load_dwordx4 v[188:191], v[238:239], off offset:256
	s_mov_b32 s100, 0x90000
	v_lshl_add_u64 v[238:239], v[254:255], 0, s[100:101]
	global_load_dwordx4 v[192:195], v[238:239], off
	global_load_dwordx4 v[196:199], v[238:239], off offset:256
	s_mov_b32 s100, 0xa0000
	v_lshl_add_u64 v[238:239], v[254:255], 0, s[100:101]
	global_load_dwordx4 v[200:203], v[238:239], off
	global_load_dwordx4 v[204:207], v[238:239], off offset:256
	s_mov_b32 s100, 0xb0000
	v_lshl_add_u64 v[238:239], v[254:255], 0, s[100:101]
	global_load_dwordx4 v[208:211], v[238:239], off
	global_load_dwordx4 v[212:215], v[238:239], off offset:256
	v_lshlrev_b32_e32 v244, 2, v150
	v_lshlrev_b32_e32 v245, 2, v151
	v_permlane16_swap_b32_e32 v124, v120
	v_permlane16_swap_b32_e32 v125, v121
	v_permlane16_swap_b32_e32 v126, v122
	v_permlane16_swap_b32_e32 v127, v123
	v_permlane16_swap_b32_e32 v116, v112
	v_permlane16_swap_b32_e32 v117, v113
	v_permlane16_swap_b32_e32 v118, v114
	v_permlane16_swap_b32_e32 v119, v115
	v_permlane16_swap_b32_e32 v108, v104
	v_permlane16_swap_b32_e32 v109, v105
	v_permlane16_swap_b32_e32 v110, v106
	v_permlane16_swap_b32_e32 v111, v107
	v_permlane16_swap_b32_e32 v100, v96
	v_permlane16_swap_b32_e32 v101, v97
	v_permlane16_swap_b32_e32 v102, v98
	v_permlane16_swap_b32_e32 v103, v99
	v_permlane16_swap_b32_e32 v92, v88
	v_permlane16_swap_b32_e32 v93, v89
	v_permlane16_swap_b32_e32 v94, v90
	v_permlane16_swap_b32_e32 v95, v91
	v_permlane16_swap_b32_e32 v84, v80
	v_permlane16_swap_b32_e32 v85, v81
	v_permlane16_swap_b32_e32 v86, v82
	v_permlane16_swap_b32_e32 v87, v83
	v_permlane16_swap_b32_e32 v76, v72
	v_permlane16_swap_b32_e32 v77, v73
	v_permlane16_swap_b32_e32 v78, v74
	v_permlane16_swap_b32_e32 v79, v75
	v_permlane16_swap_b32_e32 v68, v64
	v_permlane16_swap_b32_e32 v69, v65
	v_permlane16_swap_b32_e32 v70, v66
	v_permlane16_swap_b32_e32 v71, v67
	v_permlane16_swap_b32_e32 v60, v56
	v_permlane16_swap_b32_e32 v61, v57
	v_permlane16_swap_b32_e32 v62, v58
	v_permlane16_swap_b32_e32 v63, v59
	v_permlane16_swap_b32_e32 v52, v48
	v_permlane16_swap_b32_e32 v53, v49
	v_permlane16_swap_b32_e32 v54, v50
	v_permlane16_swap_b32_e32 v55, v51
	v_permlane16_swap_b32_e32 v44, v40
	v_permlane16_swap_b32_e32 v45, v41
	v_permlane16_swap_b32_e32 v46, v42
	v_permlane16_swap_b32_e32 v47, v43
	v_permlane16_swap_b32_e32 v36, v32
	v_permlane16_swap_b32_e32 v37, v33
	v_permlane16_swap_b32_e32 v38, v34
	v_permlane16_swap_b32_e32 v39, v35
	v_permlane16_swap_b32_e32 v28, v24
	v_permlane16_swap_b32_e32 v29, v25
	v_permlane16_swap_b32_e32 v30, v26
	v_permlane16_swap_b32_e32 v31, v27
	v_permlane16_swap_b32_e32 v20, v16
	v_permlane16_swap_b32_e32 v21, v17
	v_permlane16_swap_b32_e32 v22, v18
	v_permlane16_swap_b32_e32 v23, v19
	v_permlane16_swap_b32_e32 v12, v8
	v_permlane16_swap_b32_e32 v13, v9
	v_permlane16_swap_b32_e32 v14, v10
	v_permlane16_swap_b32_e32 v15, v11
	v_permlane16_swap_b32_e32 v4, v0
	v_permlane16_swap_b32_e32 v5, v1
	v_permlane16_swap_b32_e32 v6, v2
	v_permlane16_swap_b32_e32 v7, v3
	s_waitcnt vmcnt(14)
	ds_bpermute_b32 v140, v253, v140
	ds_bpermute_b32 v141, v253, v141
	ds_bpermute_b32 v142, v253, v142
	ds_bpermute_b32 v143, v253, v143
	ds_bpermute_b32 v154, v253, v154
	ds_bpermute_b32 v155, v253, v155
	ds_bpermute_b32 v156, v253, v156
	ds_bpermute_b32 v157, v253, v157
	s_waitcnt lgkmcnt(0)
	v_lshlrev_b32_e32 v246, 16, v140
	v_and_b32_e32 v247, 0xffff0000, v140
	v_add_f32_e32 v124, v124, v246
	v_add_f32_e32 v125, v125, v247
	v_mul_f32_e32 v248, v124, v124
	v_fmac_f32_e32 v248, v125, v125
	v_cvt_pk_bf16_f32 v140, v124, v125
	v_lshlrev_b32_e32 v246, 16, v141
	v_and_b32_e32 v247, 0xffff0000, v141
	v_add_f32_e32 v126, v126, v246
	v_add_f32_e32 v127, v127, v247
	v_fmac_f32_e32 v248, v126, v126
	v_fmac_f32_e32 v248, v127, v127
	v_cvt_pk_bf16_f32 v141, v126, v127
	v_lshlrev_b32_e32 v246, 16, v142
	v_and_b32_e32 v247, 0xffff0000, v142
	v_add_f32_e32 v120, v120, v246
	v_add_f32_e32 v121, v121, v247
	v_fmac_f32_e32 v248, v120, v120
	v_fmac_f32_e32 v248, v121, v121
	v_cvt_pk_bf16_f32 v142, v120, v121
	v_lshlrev_b32_e32 v246, 16, v143
	v_and_b32_e32 v247, 0xffff0000, v143
	v_add_f32_e32 v122, v122, v246
	v_add_f32_e32 v123, v123, v247
	v_fmac_f32_e32 v248, v122, v122
	v_fmac_f32_e32 v248, v123, v123
	v_cvt_pk_bf16_f32 v143, v122, v123
	ds_bpermute_b32 v250, v252, v236
	ds_bpermute_b32 v251, v252, v237
	ds_bpermute_b32 v140, v252, v140
	ds_bpermute_b32 v141, v252, v141
	ds_bpermute_b32 v142, v252, v142
	ds_bpermute_b32 v143, v252, v143
	s_waitcnt lgkmcnt(0)
	global_store_dwordx4 v[250:251], v[140:143], off
	v_lshlrev_b32_e32 v246, 16, v154
	v_and_b32_e32 v247, 0xffff0000, v154
	v_add_f32_e32 v116, v116, v246
	v_add_f32_e32 v117, v117, v247
	v_fmac_f32_e32 v248, v116, v116
	v_fmac_f32_e32 v248, v117, v117
	v_cvt_pk_bf16_f32 v154, v116, v117
	v_lshlrev_b32_e32 v246, 16, v155
	v_and_b32_e32 v247, 0xffff0000, v155
	v_add_f32_e32 v118, v118, v246
	v_add_f32_e32 v119, v119, v247
	v_fmac_f32_e32 v248, v118, v118
	v_fmac_f32_e32 v248, v119, v119
	v_cvt_pk_bf16_f32 v155, v118, v119
	v_lshlrev_b32_e32 v246, 16, v156
	v_and_b32_e32 v247, 0xffff0000, v156
	v_add_f32_e32 v112, v112, v246
	v_add_f32_e32 v113, v113, v247
	v_fmac_f32_e32 v248, v112, v112
	v_fmac_f32_e32 v248, v113, v113
	v_cvt_pk_bf16_f32 v156, v112, v113
	v_lshlrev_b32_e32 v246, 16, v157
	v_and_b32_e32 v247, 0xffff0000, v157
	v_add_f32_e32 v114, v114, v246
	v_add_f32_e32 v115, v115, v247
	v_fmac_f32_e32 v248, v114, v114
	v_fmac_f32_e32 v248, v115, v115
	v_cvt_pk_bf16_f32 v157, v114, v115
	ds_bpermute_b32 v154, v252, v154
	ds_bpermute_b32 v155, v252, v155
	ds_bpermute_b32 v156, v252, v156
	ds_bpermute_b32 v157, v252, v157
	s_waitcnt lgkmcnt(0)
	global_store_dwordx4 v[250:251], v[154:157], off offset:256
	s_waitcnt vmcnt(14)
	ds_bpermute_b32 v158, v253, v158
	ds_bpermute_b32 v159, v253, v159
	ds_bpermute_b32 v160, v253, v160
	ds_bpermute_b32 v161, v253, v161
	ds_bpermute_b32 v162, v253, v162
	ds_bpermute_b32 v163, v253, v163
	ds_bpermute_b32 v164, v253, v164
	ds_bpermute_b32 v165, v253, v165
	s_waitcnt lgkmcnt(0)
	s_mov_b32 s100, 0x10000
	v_lshl_add_u64 v[238:239], v[236:237], 0, s[100:101]
	v_lshlrev_b32_e32 v246, 16, v158
	v_and_b32_e32 v247, 0xffff0000, v158
	v_add_f32_e32 v108, v108, v246
	v_add_f32_e32 v109, v109, v247
	v_mul_f32_e32 v124, v108, v108
	v_fmac_f32_e32 v124, v109, v109
	v_cvt_pk_bf16_f32 v158, v108, v109
	v_lshlrev_b32_e32 v246, 16, v159
	v_and_b32_e32 v247, 0xffff0000, v159
	v_add_f32_e32 v110, v110, v246
	v_add_f32_e32 v111, v111, v247
	v_fmac_f32_e32 v124, v110, v110
	v_fmac_f32_e32 v124, v111, v111
	v_cvt_pk_bf16_f32 v159, v110, v111
	v_lshlrev_b32_e32 v246, 16, v160
	v_and_b32_e32 v247, 0xffff0000, v160
	v_add_f32_e32 v104, v104, v246
	v_add_f32_e32 v105, v105, v247
	v_fmac_f32_e32 v124, v104, v104
	v_fmac_f32_e32 v124, v105, v105
	v_cvt_pk_bf16_f32 v160, v104, v105
	v_lshlrev_b32_e32 v246, 16, v161
	v_and_b32_e32 v247, 0xffff0000, v161
	v_add_f32_e32 v106, v106, v246
	v_add_f32_e32 v107, v107, v247
	v_fmac_f32_e32 v124, v106, v106
	v_fmac_f32_e32 v124, v107, v107
	v_cvt_pk_bf16_f32 v161, v106, v107
	ds_bpermute_b32 v250, v252, v238
	ds_bpermute_b32 v251, v252, v239
	ds_bpermute_b32 v158, v252, v158
	ds_bpermute_b32 v159, v252, v159
	ds_bpermute_b32 v160, v252, v160
	ds_bpermute_b32 v161, v252, v161
	s_waitcnt lgkmcnt(0)
	global_store_dwordx4 v[250:251], v[158:161], off
	v_lshlrev_b32_e32 v246, 16, v162
	v_and_b32_e32 v247, 0xffff0000, v162
	v_add_f32_e32 v100, v100, v246
	v_add_f32_e32 v101, v101, v247
	v_fmac_f32_e32 v124, v100, v100
	v_fmac_f32_e32 v124, v101, v101
	v_cvt_pk_bf16_f32 v162, v100, v101
	v_lshlrev_b32_e32 v246, 16, v163
	v_and_b32_e32 v247, 0xffff0000, v163
	v_add_f32_e32 v102, v102, v246
	v_add_f32_e32 v103, v103, v247
	v_fmac_f32_e32 v124, v102, v102
	v_fmac_f32_e32 v124, v103, v103
	v_cvt_pk_bf16_f32 v163, v102, v103
	v_lshlrev_b32_e32 v246, 16, v164
	v_and_b32_e32 v247, 0xffff0000, v164
	v_add_f32_e32 v96, v96, v246
	v_add_f32_e32 v97, v97, v247
	v_fmac_f32_e32 v124, v96, v96
	v_fmac_f32_e32 v124, v97, v97
	v_cvt_pk_bf16_f32 v164, v96, v97
	v_lshlrev_b32_e32 v246, 16, v165
	v_and_b32_e32 v247, 0xffff0000, v165
	v_add_f32_e32 v98, v98, v246
	v_add_f32_e32 v99, v99, v247
	v_fmac_f32_e32 v124, v98, v98
	v_fmac_f32_e32 v124, v99, v99
	v_cvt_pk_bf16_f32 v165, v98, v99
	ds_bpermute_b32 v162, v252, v162
	ds_bpermute_b32 v163, v252, v163
	ds_bpermute_b32 v164, v252, v164
	ds_bpermute_b32 v165, v252, v165
	s_waitcnt lgkmcnt(0)
	global_store_dwordx4 v[250:251], v[162:165], off offset:256
	s_waitcnt vmcnt(14)
	ds_bpermute_b32 v166, v253, v166
	ds_bpermute_b32 v167, v253, v167
	ds_bpermute_b32 v168, v253, v168
	ds_bpermute_b32 v169, v253, v169
	ds_bpermute_b32 v170, v253, v170
	ds_bpermute_b32 v171, v253, v171
	ds_bpermute_b32 v172, v253, v172
	ds_bpermute_b32 v173, v253, v173
	s_waitcnt lgkmcnt(0)
	s_mov_b32 s100, 0x20000
	v_lshl_add_u64 v[238:239], v[236:237], 0, s[100:101]
	v_lshlrev_b32_e32 v246, 16, v166
	v_and_b32_e32 v247, 0xffff0000, v166
	v_add_f32_e32 v92, v92, v246
	v_add_f32_e32 v93, v93, v247
	v_mul_f32_e32 v108, v92, v92
	v_fmac_f32_e32 v108, v93, v93
	v_cvt_pk_bf16_f32 v166, v92, v93
	v_lshlrev_b32_e32 v246, 16, v167
	v_and_b32_e32 v247, 0xffff0000, v167
	v_add_f32_e32 v94, v94, v246
	v_add_f32_e32 v95, v95, v247
	v_fmac_f32_e32 v108, v94, v94
	v_fmac_f32_e32 v108, v95, v95
	v_cvt_pk_bf16_f32 v167, v94, v95
	v_lshlrev_b32_e32 v246, 16, v168
	v_and_b32_e32 v247, 0xffff0000, v168
	v_add_f32_e32 v88, v88, v246
	v_add_f32_e32 v89, v89, v247
	v_fmac_f32_e32 v108, v88, v88
	v_fmac_f32_e32 v108, v89, v89
	v_cvt_pk_bf16_f32 v168, v88, v89
	v_lshlrev_b32_e32 v246, 16, v169
	v_and_b32_e32 v247, 0xffff0000, v169
	v_add_f32_e32 v90, v90, v246
	v_add_f32_e32 v91, v91, v247
	v_fmac_f32_e32 v108, v90, v90
	v_fmac_f32_e32 v108, v91, v91
	v_cvt_pk_bf16_f32 v169, v90, v91
	ds_bpermute_b32 v250, v252, v238
	ds_bpermute_b32 v251, v252, v239
	ds_bpermute_b32 v166, v252, v166
	ds_bpermute_b32 v167, v252, v167
	ds_bpermute_b32 v168, v252, v168
	ds_bpermute_b32 v169, v252, v169
	s_waitcnt lgkmcnt(0)
	global_store_dwordx4 v[250:251], v[166:169], off
	v_lshlrev_b32_e32 v246, 16, v170
	v_and_b32_e32 v247, 0xffff0000, v170
	v_add_f32_e32 v84, v84, v246
	v_add_f32_e32 v85, v85, v247
	v_fmac_f32_e32 v108, v84, v84
	v_fmac_f32_e32 v108, v85, v85
	v_cvt_pk_bf16_f32 v170, v84, v85
	v_lshlrev_b32_e32 v246, 16, v171
	v_and_b32_e32 v247, 0xffff0000, v171
	v_add_f32_e32 v86, v86, v246
	v_add_f32_e32 v87, v87, v247
	v_fmac_f32_e32 v108, v86, v86
	v_fmac_f32_e32 v108, v87, v87
	v_cvt_pk_bf16_f32 v171, v86, v87
	v_lshlrev_b32_e32 v246, 16, v172
	v_and_b32_e32 v247, 0xffff0000, v172
	v_add_f32_e32 v80, v80, v246
	v_add_f32_e32 v81, v81, v247
	v_fmac_f32_e32 v108, v80, v80
	v_fmac_f32_e32 v108, v81, v81
	v_cvt_pk_bf16_f32 v172, v80, v81
	v_lshlrev_b32_e32 v246, 16, v173
	v_and_b32_e32 v247, 0xffff0000, v173
	v_add_f32_e32 v82, v82, v246
	v_add_f32_e32 v83, v83, v247
	v_fmac_f32_e32 v108, v82, v82
	v_fmac_f32_e32 v108, v83, v83
	v_cvt_pk_bf16_f32 v173, v82, v83
	ds_bpermute_b32 v170, v252, v170
	ds_bpermute_b32 v171, v252, v171
	ds_bpermute_b32 v172, v252, v172
	ds_bpermute_b32 v173, v252, v173
	s_waitcnt lgkmcnt(0)
	global_store_dwordx4 v[250:251], v[170:173], off offset:256
	s_waitcnt vmcnt(14)
	ds_bpermute_b32 v174, v253, v174
	ds_bpermute_b32 v175, v253, v175
	ds_bpermute_b32 v176, v253, v176
	ds_bpermute_b32 v177, v253, v177
	ds_bpermute_b32 v178, v253, v178
	ds_bpermute_b32 v179, v253, v179
	ds_bpermute_b32 v180, v253, v180
	ds_bpermute_b32 v181, v253, v181
	s_waitcnt lgkmcnt(0)
	s_mov_b32 s100, 0x30000
	v_lshl_add_u64 v[238:239], v[236:237], 0, s[100:101]
	v_lshlrev_b32_e32 v246, 16, v174
	v_and_b32_e32 v247, 0xffff0000, v174
	v_add_f32_e32 v76, v76, v246
	v_add_f32_e32 v77, v77, v247
	v_mul_f32_e32 v92, v76, v76
	v_fmac_f32_e32 v92, v77, v77
	v_cvt_pk_bf16_f32 v174, v76, v77
	v_lshlrev_b32_e32 v246, 16, v175
	v_and_b32_e32 v247, 0xffff0000, v175
	v_add_f32_e32 v78, v78, v246
	v_add_f32_e32 v79, v79, v247
	v_fmac_f32_e32 v92, v78, v78
	v_fmac_f32_e32 v92, v79, v79
	v_cvt_pk_bf16_f32 v175, v78, v79
	v_lshlrev_b32_e32 v246, 16, v176
	v_and_b32_e32 v247, 0xffff0000, v176
	v_add_f32_e32 v72, v72, v246
	v_add_f32_e32 v73, v73, v247
	v_fmac_f32_e32 v92, v72, v72
	v_fmac_f32_e32 v92, v73, v73
	v_cvt_pk_bf16_f32 v176, v72, v73
	v_lshlrev_b32_e32 v246, 16, v177
	v_and_b32_e32 v247, 0xffff0000, v177
	v_add_f32_e32 v74, v74, v246
	v_add_f32_e32 v75, v75, v247
	v_fmac_f32_e32 v92, v74, v74
	v_fmac_f32_e32 v92, v75, v75
	v_cvt_pk_bf16_f32 v177, v74, v75
	ds_bpermute_b32 v250, v252, v238
	ds_bpermute_b32 v251, v252, v239
	ds_bpermute_b32 v174, v252, v174
	ds_bpermute_b32 v175, v252, v175
	ds_bpermute_b32 v176, v252, v176
	ds_bpermute_b32 v177, v252, v177
	s_waitcnt lgkmcnt(0)
	global_store_dwordx4 v[250:251], v[174:177], off
	v_lshlrev_b32_e32 v246, 16, v178
	v_and_b32_e32 v247, 0xffff0000, v178
	v_add_f32_e32 v68, v68, v246
	v_add_f32_e32 v69, v69, v247
	v_fmac_f32_e32 v92, v68, v68
	v_fmac_f32_e32 v92, v69, v69
	v_cvt_pk_bf16_f32 v178, v68, v69
	v_lshlrev_b32_e32 v246, 16, v179
	v_and_b32_e32 v247, 0xffff0000, v179
	v_add_f32_e32 v70, v70, v246
	v_add_f32_e32 v71, v71, v247
	v_fmac_f32_e32 v92, v70, v70
	v_fmac_f32_e32 v92, v71, v71
	v_cvt_pk_bf16_f32 v179, v70, v71
	v_lshlrev_b32_e32 v246, 16, v180
	v_and_b32_e32 v247, 0xffff0000, v180
	v_add_f32_e32 v64, v64, v246
	v_add_f32_e32 v65, v65, v247
	v_fmac_f32_e32 v92, v64, v64
	v_fmac_f32_e32 v92, v65, v65
	v_cvt_pk_bf16_f32 v180, v64, v65
	v_lshlrev_b32_e32 v246, 16, v181
	v_and_b32_e32 v247, 0xffff0000, v181
	v_add_f32_e32 v66, v66, v246
	v_add_f32_e32 v67, v67, v247
	v_fmac_f32_e32 v92, v66, v66
	v_fmac_f32_e32 v92, v67, v67
	v_cvt_pk_bf16_f32 v181, v66, v67
	ds_bpermute_b32 v178, v252, v178
	ds_bpermute_b32 v179, v252, v179
	ds_bpermute_b32 v180, v252, v180
	ds_bpermute_b32 v181, v252, v181
	s_waitcnt lgkmcnt(0)
	global_store_dwordx4 v[250:251], v[178:181], off offset:256
	s_waitcnt vmcnt(14)
	ds_bpermute_b32 v184, v253, v184
	ds_bpermute_b32 v185, v253, v185
	ds_bpermute_b32 v186, v253, v186
	ds_bpermute_b32 v187, v253, v187
	ds_bpermute_b32 v188, v253, v188
	ds_bpermute_b32 v189, v253, v189
	ds_bpermute_b32 v190, v253, v190
	ds_bpermute_b32 v191, v253, v191
	s_waitcnt lgkmcnt(0)
	s_mov_b32 s100, 0x80000
	v_lshl_add_u64 v[238:239], v[236:237], 0, s[100:101]
	v_lshlrev_b32_e32 v246, 16, v184
	v_and_b32_e32 v247, 0xffff0000, v184
	v_add_f32_e32 v60, v60, v246
	v_add_f32_e32 v61, v61, v247
	v_mul_f32_e32 v76, v60, v60
	v_fmac_f32_e32 v76, v61, v61
	v_cvt_pk_bf16_f32 v184, v60, v61
	v_lshlrev_b32_e32 v246, 16, v185
	v_and_b32_e32 v247, 0xffff0000, v185
	v_add_f32_e32 v62, v62, v246
	v_add_f32_e32 v63, v63, v247
	v_fmac_f32_e32 v76, v62, v62
	v_fmac_f32_e32 v76, v63, v63
	v_cvt_pk_bf16_f32 v185, v62, v63
	v_lshlrev_b32_e32 v246, 16, v186
	v_and_b32_e32 v247, 0xffff0000, v186
	v_add_f32_e32 v56, v56, v246
	v_add_f32_e32 v57, v57, v247
	v_fmac_f32_e32 v76, v56, v56
	v_fmac_f32_e32 v76, v57, v57
	v_cvt_pk_bf16_f32 v186, v56, v57
	v_lshlrev_b32_e32 v246, 16, v187
	v_and_b32_e32 v247, 0xffff0000, v187
	v_add_f32_e32 v58, v58, v246
	v_add_f32_e32 v59, v59, v247
	v_fmac_f32_e32 v76, v58, v58
	v_fmac_f32_e32 v76, v59, v59
	v_cvt_pk_bf16_f32 v187, v58, v59
	ds_bpermute_b32 v250, v252, v238
	ds_bpermute_b32 v251, v252, v239
	ds_bpermute_b32 v184, v252, v184
	ds_bpermute_b32 v185, v252, v185
	ds_bpermute_b32 v186, v252, v186
	ds_bpermute_b32 v187, v252, v187
	s_waitcnt lgkmcnt(0)
	global_store_dwordx4 v[250:251], v[184:187], off
	v_lshlrev_b32_e32 v246, 16, v188
	v_and_b32_e32 v247, 0xffff0000, v188
	v_add_f32_e32 v52, v52, v246
	v_add_f32_e32 v53, v53, v247
	v_fmac_f32_e32 v76, v52, v52
	v_fmac_f32_e32 v76, v53, v53
	v_cvt_pk_bf16_f32 v188, v52, v53
	v_lshlrev_b32_e32 v246, 16, v189
	v_and_b32_e32 v247, 0xffff0000, v189
	v_add_f32_e32 v54, v54, v246
	v_add_f32_e32 v55, v55, v247
	v_fmac_f32_e32 v76, v54, v54
	v_fmac_f32_e32 v76, v55, v55
	v_cvt_pk_bf16_f32 v189, v54, v55
	v_lshlrev_b32_e32 v246, 16, v190
	v_and_b32_e32 v247, 0xffff0000, v190
	v_add_f32_e32 v48, v48, v246
	v_add_f32_e32 v49, v49, v247
	v_fmac_f32_e32 v76, v48, v48
	v_fmac_f32_e32 v76, v49, v49
	v_cvt_pk_bf16_f32 v190, v48, v49
	v_lshlrev_b32_e32 v246, 16, v191
	v_and_b32_e32 v247, 0xffff0000, v191
	v_add_f32_e32 v50, v50, v246
	v_add_f32_e32 v51, v51, v247
	v_fmac_f32_e32 v76, v50, v50
	v_fmac_f32_e32 v76, v51, v51
	v_cvt_pk_bf16_f32 v191, v50, v51
	ds_bpermute_b32 v188, v252, v188
	ds_bpermute_b32 v189, v252, v189
	ds_bpermute_b32 v190, v252, v190
	ds_bpermute_b32 v191, v252, v191
	s_waitcnt lgkmcnt(0)
	global_store_dwordx4 v[250:251], v[188:191], off offset:256
	s_waitcnt vmcnt(14)
	ds_bpermute_b32 v192, v253, v192
	ds_bpermute_b32 v193, v253, v193
	ds_bpermute_b32 v194, v253, v194
	ds_bpermute_b32 v195, v253, v195
	ds_bpermute_b32 v196, v253, v196
	ds_bpermute_b32 v197, v253, v197
	ds_bpermute_b32 v198, v253, v198
	ds_bpermute_b32 v199, v253, v199
	s_waitcnt lgkmcnt(0)
	s_mov_b32 s100, 0x90000
	v_lshl_add_u64 v[238:239], v[236:237], 0, s[100:101]
	v_lshlrev_b32_e32 v246, 16, v192
	v_and_b32_e32 v247, 0xffff0000, v192
	v_add_f32_e32 v44, v44, v246
	v_add_f32_e32 v45, v45, v247
	v_mul_f32_e32 v60, v44, v44
	v_fmac_f32_e32 v60, v45, v45
	v_cvt_pk_bf16_f32 v192, v44, v45
	v_lshlrev_b32_e32 v246, 16, v193
	v_and_b32_e32 v247, 0xffff0000, v193
	v_add_f32_e32 v46, v46, v246
	v_add_f32_e32 v47, v47, v247
	v_fmac_f32_e32 v60, v46, v46
	v_fmac_f32_e32 v60, v47, v47
	v_cvt_pk_bf16_f32 v193, v46, v47
	v_lshlrev_b32_e32 v246, 16, v194
	v_and_b32_e32 v247, 0xffff0000, v194
	v_add_f32_e32 v40, v40, v246
	v_add_f32_e32 v41, v41, v247
	v_fmac_f32_e32 v60, v40, v40
	v_fmac_f32_e32 v60, v41, v41
	v_cvt_pk_bf16_f32 v194, v40, v41
	v_lshlrev_b32_e32 v246, 16, v195
	v_and_b32_e32 v247, 0xffff0000, v195
	v_add_f32_e32 v42, v42, v246
	v_add_f32_e32 v43, v43, v247
	v_fmac_f32_e32 v60, v42, v42
	v_fmac_f32_e32 v60, v43, v43
	v_cvt_pk_bf16_f32 v195, v42, v43
	ds_bpermute_b32 v250, v252, v238
	ds_bpermute_b32 v251, v252, v239
	ds_bpermute_b32 v192, v252, v192
	ds_bpermute_b32 v193, v252, v193
	ds_bpermute_b32 v194, v252, v194
	ds_bpermute_b32 v195, v252, v195
	s_waitcnt lgkmcnt(0)
	global_store_dwordx4 v[250:251], v[192:195], off
	v_lshlrev_b32_e32 v246, 16, v196
	v_and_b32_e32 v247, 0xffff0000, v196
	v_add_f32_e32 v36, v36, v246
	v_add_f32_e32 v37, v37, v247
	v_fmac_f32_e32 v60, v36, v36
	v_fmac_f32_e32 v60, v37, v37
	v_cvt_pk_bf16_f32 v196, v36, v37
	v_lshlrev_b32_e32 v246, 16, v197
	v_and_b32_e32 v247, 0xffff0000, v197
	v_add_f32_e32 v38, v38, v246
	v_add_f32_e32 v39, v39, v247
	v_fmac_f32_e32 v60, v38, v38
	v_fmac_f32_e32 v60, v39, v39
	v_cvt_pk_bf16_f32 v197, v38, v39
	v_lshlrev_b32_e32 v246, 16, v198
	v_and_b32_e32 v247, 0xffff0000, v198
	v_add_f32_e32 v32, v32, v246
	v_add_f32_e32 v33, v33, v247
	v_fmac_f32_e32 v60, v32, v32
	v_fmac_f32_e32 v60, v33, v33
	v_cvt_pk_bf16_f32 v198, v32, v33
	v_lshlrev_b32_e32 v246, 16, v199
	v_and_b32_e32 v247, 0xffff0000, v199
	v_add_f32_e32 v34, v34, v246
	v_add_f32_e32 v35, v35, v247
	v_fmac_f32_e32 v60, v34, v34
	v_fmac_f32_e32 v60, v35, v35
	v_cvt_pk_bf16_f32 v199, v34, v35
	ds_bpermute_b32 v196, v252, v196
	ds_bpermute_b32 v197, v252, v197
	ds_bpermute_b32 v198, v252, v198
	ds_bpermute_b32 v199, v252, v199
	s_waitcnt lgkmcnt(0)
	global_store_dwordx4 v[250:251], v[196:199], off offset:256
	s_waitcnt vmcnt(14)
	ds_bpermute_b32 v200, v253, v200
	ds_bpermute_b32 v201, v253, v201
	ds_bpermute_b32 v202, v253, v202
	ds_bpermute_b32 v203, v253, v203
	ds_bpermute_b32 v204, v253, v204
	ds_bpermute_b32 v205, v253, v205
	ds_bpermute_b32 v206, v253, v206
	ds_bpermute_b32 v207, v253, v207
	s_waitcnt lgkmcnt(0)
	s_mov_b32 s100, 0xa0000
	v_lshl_add_u64 v[238:239], v[236:237], 0, s[100:101]
	v_lshlrev_b32_e32 v246, 16, v200
	v_and_b32_e32 v247, 0xffff0000, v200
	v_add_f32_e32 v28, v28, v246
	v_add_f32_e32 v29, v29, v247
	v_mul_f32_e32 v44, v28, v28
	v_fmac_f32_e32 v44, v29, v29
	v_cvt_pk_bf16_f32 v200, v28, v29
	v_lshlrev_b32_e32 v246, 16, v201
	v_and_b32_e32 v247, 0xffff0000, v201
	v_add_f32_e32 v30, v30, v246
	v_add_f32_e32 v31, v31, v247
	v_fmac_f32_e32 v44, v30, v30
	v_fmac_f32_e32 v44, v31, v31
	v_cvt_pk_bf16_f32 v201, v30, v31
	v_lshlrev_b32_e32 v246, 16, v202
	v_and_b32_e32 v247, 0xffff0000, v202
	v_add_f32_e32 v24, v24, v246
	v_add_f32_e32 v25, v25, v247
	v_fmac_f32_e32 v44, v24, v24
	v_fmac_f32_e32 v44, v25, v25
	v_cvt_pk_bf16_f32 v202, v24, v25
	v_lshlrev_b32_e32 v246, 16, v203
	v_and_b32_e32 v247, 0xffff0000, v203
	v_add_f32_e32 v26, v26, v246
	v_add_f32_e32 v27, v27, v247
	v_fmac_f32_e32 v44, v26, v26
	v_fmac_f32_e32 v44, v27, v27
	v_cvt_pk_bf16_f32 v203, v26, v27
	ds_bpermute_b32 v250, v252, v238
	ds_bpermute_b32 v251, v252, v239
	ds_bpermute_b32 v200, v252, v200
	ds_bpermute_b32 v201, v252, v201
	ds_bpermute_b32 v202, v252, v202
	ds_bpermute_b32 v203, v252, v203
	s_waitcnt lgkmcnt(0)
	global_store_dwordx4 v[250:251], v[200:203], off
	v_lshlrev_b32_e32 v246, 16, v204
	v_and_b32_e32 v247, 0xffff0000, v204
	v_add_f32_e32 v20, v20, v246
	v_add_f32_e32 v21, v21, v247
	v_fmac_f32_e32 v44, v20, v20
	v_fmac_f32_e32 v44, v21, v21
	v_cvt_pk_bf16_f32 v204, v20, v21
	v_lshlrev_b32_e32 v246, 16, v205
	v_and_b32_e32 v247, 0xffff0000, v205
	v_add_f32_e32 v22, v22, v246
	v_add_f32_e32 v23, v23, v247
	v_fmac_f32_e32 v44, v22, v22
	v_fmac_f32_e32 v44, v23, v23
	v_cvt_pk_bf16_f32 v205, v22, v23
	v_lshlrev_b32_e32 v246, 16, v206
	v_and_b32_e32 v247, 0xffff0000, v206
	v_add_f32_e32 v16, v16, v246
	v_add_f32_e32 v17, v17, v247
	v_fmac_f32_e32 v44, v16, v16
	v_fmac_f32_e32 v44, v17, v17
	v_cvt_pk_bf16_f32 v206, v16, v17
	v_lshlrev_b32_e32 v246, 16, v207
	v_and_b32_e32 v247, 0xffff0000, v207
	v_add_f32_e32 v18, v18, v246
	v_add_f32_e32 v19, v19, v247
	v_fmac_f32_e32 v44, v18, v18
	v_fmac_f32_e32 v44, v19, v19
	v_cvt_pk_bf16_f32 v207, v18, v19
	ds_bpermute_b32 v204, v252, v204
	ds_bpermute_b32 v205, v252, v205
	ds_bpermute_b32 v206, v252, v206
	ds_bpermute_b32 v207, v252, v207
	s_waitcnt lgkmcnt(0)
	global_store_dwordx4 v[250:251], v[204:207], off offset:256
	s_waitcnt vmcnt(14)
	ds_bpermute_b32 v208, v253, v208
	ds_bpermute_b32 v209, v253, v209
	ds_bpermute_b32 v210, v253, v210
	ds_bpermute_b32 v211, v253, v211
	ds_bpermute_b32 v212, v253, v212
	ds_bpermute_b32 v213, v253, v213
	ds_bpermute_b32 v214, v253, v214
	ds_bpermute_b32 v215, v253, v215
	s_waitcnt lgkmcnt(0)
	s_mov_b32 s100, 0xb0000
	v_lshl_add_u64 v[238:239], v[236:237], 0, s[100:101]
	v_lshlrev_b32_e32 v246, 16, v208
	v_and_b32_e32 v247, 0xffff0000, v208
	v_add_f32_e32 v12, v12, v246
	v_add_f32_e32 v13, v13, v247
	v_mul_f32_e32 v28, v12, v12
	v_fmac_f32_e32 v28, v13, v13
	v_cvt_pk_bf16_f32 v208, v12, v13
	v_lshlrev_b32_e32 v246, 16, v209
	v_and_b32_e32 v247, 0xffff0000, v209
	v_add_f32_e32 v14, v14, v246
	v_add_f32_e32 v15, v15, v247
	v_fmac_f32_e32 v28, v14, v14
	v_fmac_f32_e32 v28, v15, v15
	v_cvt_pk_bf16_f32 v209, v14, v15
	v_lshlrev_b32_e32 v246, 16, v210
	v_and_b32_e32 v247, 0xffff0000, v210
	v_add_f32_e32 v8, v8, v246
	v_add_f32_e32 v9, v9, v247
	v_fmac_f32_e32 v28, v8, v8
	v_fmac_f32_e32 v28, v9, v9
	v_cvt_pk_bf16_f32 v210, v8, v9
	v_lshlrev_b32_e32 v246, 16, v211
	v_and_b32_e32 v247, 0xffff0000, v211
	v_add_f32_e32 v10, v10, v246
	v_add_f32_e32 v11, v11, v247
	v_fmac_f32_e32 v28, v10, v10
	v_fmac_f32_e32 v28, v11, v11
	v_cvt_pk_bf16_f32 v211, v10, v11
	ds_bpermute_b32 v250, v252, v238
	ds_bpermute_b32 v251, v252, v239
	ds_bpermute_b32 v208, v252, v208
	ds_bpermute_b32 v209, v252, v209
	ds_bpermute_b32 v210, v252, v210
	ds_bpermute_b32 v211, v252, v211
	s_waitcnt lgkmcnt(0)
	global_store_dwordx4 v[250:251], v[208:211], off
	v_lshlrev_b32_e32 v246, 16, v212
	v_and_b32_e32 v247, 0xffff0000, v212
	v_add_f32_e32 v4, v4, v246
	v_add_f32_e32 v5, v5, v247
	v_fmac_f32_e32 v28, v4, v4
	v_fmac_f32_e32 v28, v5, v5
	v_cvt_pk_bf16_f32 v212, v4, v5
	v_lshlrev_b32_e32 v246, 16, v213
	v_and_b32_e32 v247, 0xffff0000, v213
	v_add_f32_e32 v6, v6, v246
	v_add_f32_e32 v7, v7, v247
	v_fmac_f32_e32 v28, v6, v6
	v_fmac_f32_e32 v28, v7, v7
	v_cvt_pk_bf16_f32 v213, v6, v7
	v_lshlrev_b32_e32 v246, 16, v214
	v_and_b32_e32 v247, 0xffff0000, v214
	v_add_f32_e32 v0, v0, v246
	v_add_f32_e32 v1, v1, v247
	v_fmac_f32_e32 v28, v0, v0
	v_fmac_f32_e32 v28, v1, v1
	v_cvt_pk_bf16_f32 v214, v0, v1
	v_lshlrev_b32_e32 v246, 16, v215
	v_and_b32_e32 v247, 0xffff0000, v215
	v_add_f32_e32 v2, v2, v246
	v_add_f32_e32 v3, v3, v247
	v_fmac_f32_e32 v28, v2, v2
	v_fmac_f32_e32 v28, v3, v3
	v_cvt_pk_bf16_f32 v215, v2, v3
	ds_bpermute_b32 v212, v252, v212
	ds_bpermute_b32 v213, v252, v213
	ds_bpermute_b32 v214, v252, v214
	ds_bpermute_b32 v215, v252, v215
	s_waitcnt lgkmcnt(0)
	global_store_dwordx4 v[250:251], v[212:215], off offset:256
	ds_bpermute_b32 v0, v244, v248
	ds_bpermute_b32 v1, v244, v124
	ds_bpermute_b32 v2, v244, v108
	ds_bpermute_b32 v3, v244, v92
	ds_bpermute_b32 v8, v244, v76
	ds_bpermute_b32 v9, v244, v60
	ds_bpermute_b32 v10, v244, v44
	ds_bpermute_b32 v11, v244, v28
	s_waitcnt lgkmcnt(7)
	v_add_f32_e32 v248, v248, v0
	s_waitcnt lgkmcnt(6)
	v_add_f32_e32 v124, v124, v1
	s_waitcnt lgkmcnt(5)
	v_add_f32_e32 v108, v108, v2
	s_waitcnt lgkmcnt(4)
	v_add_f32_e32 v92, v92, v3
	s_waitcnt lgkmcnt(3)
	v_add_f32_e32 v76, v76, v8
	s_waitcnt lgkmcnt(2)
	v_add_f32_e32 v60, v60, v9
	s_waitcnt lgkmcnt(1)
	v_add_f32_e32 v44, v44, v10
	s_waitcnt lgkmcnt(0)
	v_add_f32_e32 v28, v28, v11
	ds_bpermute_b32 v0, v245, v248
	ds_bpermute_b32 v1, v245, v124
	ds_bpermute_b32 v2, v245, v108
	ds_bpermute_b32 v3, v245, v92
	ds_bpermute_b32 v8, v245, v76
	ds_bpermute_b32 v9, v245, v60
	ds_bpermute_b32 v10, v245, v44
	ds_bpermute_b32 v11, v245, v28
	s_waitcnt lgkmcnt(7)
	v_add_f32_e32 v248, v248, v0
	s_waitcnt lgkmcnt(6)
	v_add_f32_e32 v124, v124, v1
	s_waitcnt lgkmcnt(5)
	v_add_f32_e32 v108, v108, v2
	s_waitcnt lgkmcnt(4)
	v_add_f32_e32 v92, v92, v3
	s_waitcnt lgkmcnt(3)
	v_add_f32_e32 v76, v76, v8
	s_waitcnt lgkmcnt(2)
	v_add_f32_e32 v60, v60, v9
	s_waitcnt lgkmcnt(1)
	v_add_f32_e32 v44, v44, v10
	s_waitcnt lgkmcnt(0)
	v_add_f32_e32 v28, v28, v11
	s_and_saveexec_b64 s[24:25], s[6:7]
	v_lshl_add_u64 v[236:237], v[240:241], 3, s[4:5]
	v_mul_f32_e32 v248, 0x4f800000, v248
	v_trunc_f32_e32 v248, v248
	v_mul_f32_e32 v0, 0x2f800000, v248
	v_floor_f32_e32 v0, v0
	v_fmac_f32_e32 v248, 0xcf800000, v0
	v_cvt_u32_f32_e32 v246, v248
	v_cvt_u32_f32_e32 v247, v0
	global_atomic_add_x2 v[236:237], v[246:247], off
	s_nop 1
	v_mul_f32_e32 v124, 0x4f800000, v124
	v_trunc_f32_e32 v124, v124
	v_mul_f32_e32 v1, 0x2f800000, v124
	v_floor_f32_e32 v1, v1
	v_fmac_f32_e32 v124, 0xcf800000, v1
	v_cvt_u32_f32_e32 v246, v124
	v_cvt_u32_f32_e32 v247, v1
	global_atomic_add_x2 v[236:237], v[246:247], off offset:128
	s_nop 1
	v_mul_f32_e32 v108, 0x4f800000, v108
	v_trunc_f32_e32 v108, v108
	v_mul_f32_e32 v2, 0x2f800000, v108
	v_floor_f32_e32 v2, v2
	v_fmac_f32_e32 v108, 0xcf800000, v2
	v_cvt_u32_f32_e32 v246, v108
	v_cvt_u32_f32_e32 v247, v2
	global_atomic_add_x2 v[236:237], v[246:247], off offset:256
	s_nop 1
	v_mul_f32_e32 v92, 0x4f800000, v92
	v_trunc_f32_e32 v92, v92
	v_mul_f32_e32 v3, 0x2f800000, v92
	v_floor_f32_e32 v3, v3
	v_fmac_f32_e32 v92, 0xcf800000, v3
	v_cvt_u32_f32_e32 v246, v92
	v_cvt_u32_f32_e32 v247, v3
	global_atomic_add_x2 v[236:237], v[246:247], off offset:384
	s_nop 1
	v_mul_f32_e32 v76, 0x4f800000, v76
	v_trunc_f32_e32 v76, v76
	v_mul_f32_e32 v8, 0x2f800000, v76
	v_floor_f32_e32 v8, v8
	v_fmac_f32_e32 v76, 0xcf800000, v8
	v_cvt_u32_f32_e32 v246, v76
	v_cvt_u32_f32_e32 v247, v8
	global_atomic_add_x2 v[236:237], v[246:247], off offset:1024
	s_nop 1
	v_mul_f32_e32 v60, 0x4f800000, v60
	v_trunc_f32_e32 v60, v60
	v_mul_f32_e32 v9, 0x2f800000, v60
	v_floor_f32_e32 v9, v9
	v_fmac_f32_e32 v60, 0xcf800000, v9
	v_cvt_u32_f32_e32 v246, v60
	v_cvt_u32_f32_e32 v247, v9
	global_atomic_add_x2 v[236:237], v[246:247], off offset:1152
	s_nop 1
	v_mul_f32_e32 v44, 0x4f800000, v44
	v_trunc_f32_e32 v44, v44
	v_mul_f32_e32 v10, 0x2f800000, v44
	v_floor_f32_e32 v10, v10
	v_fmac_f32_e32 v44, 0xcf800000, v10
	v_cvt_u32_f32_e32 v246, v44
	v_cvt_u32_f32_e32 v247, v10
	global_atomic_add_x2 v[236:237], v[246:247], off offset:1280
	s_nop 1
	v_mul_f32_e32 v28, 0x4f800000, v28
	v_trunc_f32_e32 v28, v28
	v_mul_f32_e32 v11, 0x2f800000, v28
	v_floor_f32_e32 v11, v11
	v_fmac_f32_e32 v28, 0xcf800000, v11
	v_cvt_u32_f32_e32 v246, v28
	v_cvt_u32_f32_e32 v247, v11
	global_atomic_add_x2 v[236:237], v[246:247], off offset:1408
	s_nop 1

.LBB0_2396:
	v_mbcnt_lo_u32_b32 v252, -1, 0
	v_mbcnt_hi_u32_b32 v252, -1, v252
	v_and_b32_e32 v250, 3, v252
	v_lshrrev_b32_e32 v252, 2, v252
	v_lshl_or_b32 v252, v250, 4, v252
	v_lshlrev_b32_e32 v252, 2, v252
	v_lshl_add_u32 v240, s42, 8, v144
	v_and_b32_e32 v242, 0xe0, v146
	v_and_b32_e32 v243, 4, v146
	v_lshl_or_b32 v242, v243, 2, v242
	v_and_b32_e32 v243, 8, v146
	v_or_b32_e32 v242, v242, v243
	v_lshl_or_b32 v242, s43, 8, v242
	v_mov_b32_e32 v243, 0
	v_ashrrev_i32_e32 v241, 31, v240
	v_readlane_b32 s18, v234, 22
	v_readlane_b32 s19, v234, 23
	v_lshlrev_b64 v[246:247], 11, v[240:241]
	v_lshl_add_u64 v[246:247], v[246:247], 0, v[242:243]
	v_lshl_add_u64 v[236:237], v[246:247], 1, s[18:19]
	v_mbcnt_lo_u32_b32 v253, -1, 0
	v_mbcnt_hi_u32_b32 v253, -1, v253
	v_and_b32_e32 v254, 15, v253
	v_lshrrev_b32_e32 v253, 4, v253
	v_lshl_or_b32 v253, v254, 2, v253
	v_lshlrev_b32_e32 v253, 2, v253
	ds_bpermute_b32 v254, v252, v236
	ds_bpermute_b32 v255, v252, v237
	s_waitcnt lgkmcnt(0)
	s_mov_b32 s101, 0
	global_load_dwordx4 v[140:143], v[254:255], off
	global_load_dwordx4 v[154:157], v[254:255], off offset:256
	s_mov_b32 s100, 0x10000
	v_lshl_add_u64 v[238:239], v[254:255], 0, s[100:101]
	global_load_dwordx4 v[158:161], v[238:239], off
	global_load_dwordx4 v[162:165], v[238:239], off offset:256
	s_mov_b32 s100, 0x20000
	v_lshl_add_u64 v[238:239], v[254:255], 0, s[100:101]
	global_load_dwordx4 v[166:169], v[238:239], off
	global_load_dwordx4 v[170:173], v[238:239], off offset:256
	s_mov_b32 s100, 0x30000
	v_lshl_add_u64 v[238:239], v[254:255], 0, s[100:101]
	global_load_dwordx4 v[174:177], v[238:239], off
	global_load_dwordx4 v[178:181], v[238:239], off offset:256
	s_mov_b32 s100, 0x80000
	v_lshl_add_u64 v[238:239], v[254:255], 0, s[100:101]
	global_load_dwordx4 v[184:187], v[238:239], off
	global_load_dwordx4 v[188:191], v[238:239], off offset:256
	s_mov_b32 s100, 0x90000
	v_lshl_add_u64 v[238:239], v[254:255], 0, s[100:101]
	global_load_dwordx4 v[192:195], v[238:239], off
	global_load_dwordx4 v[196:199], v[238:239], off offset:256
	s_mov_b32 s100, 0xa0000
	v_lshl_add_u64 v[238:239], v[254:255], 0, s[100:101]
	global_load_dwordx4 v[200:203], v[238:239], off
	global_load_dwordx4 v[204:207], v[238:239], off offset:256
	s_mov_b32 s100, 0xb0000
	v_lshl_add_u64 v[238:239], v[254:255], 0, s[100:101]
	global_load_dwordx4 v[208:211], v[238:239], off
	global_load_dwordx4 v[212:215], v[238:239], off offset:256
	v_lshlrev_b32_e32 v244, 2, v150
	v_lshlrev_b32_e32 v245, 2, v151
	v_permlane16_swap_b32_e32 v124, v120
	v_permlane16_swap_b32_e32 v125, v121
	v_permlane16_swap_b32_e32 v126, v122
	v_permlane16_swap_b32_e32 v127, v123
	v_permlane16_swap_b32_e32 v116, v112
	v_permlane16_swap_b32_e32 v117, v113
	v_permlane16_swap_b32_e32 v118, v114
	v_permlane16_swap_b32_e32 v119, v115
	v_permlane16_swap_b32_e32 v108, v104
	v_permlane16_swap_b32_e32 v109, v105
	v_permlane16_swap_b32_e32 v110, v106
	v_permlane16_swap_b32_e32 v111, v107
	v_permlane16_swap_b32_e32 v100, v96
	v_permlane16_swap_b32_e32 v101, v97
	v_permlane16_swap_b32_e32 v102, v98
	v_permlane16_swap_b32_e32 v103, v99
	v_permlane16_swap_b32_e32 v92, v88
	v_permlane16_swap_b32_e32 v93, v89
	v_permlane16_swap_b32_e32 v94, v90
	v_permlane16_swap_b32_e32 v95, v91
	v_permlane16_swap_b32_e32 v84, v80
	v_permlane16_swap_b32_e32 v85, v81
	v_permlane16_swap_b32_e32 v86, v82
	v_permlane16_swap_b32_e32 v87, v83
	v_permlane16_swap_b32_e32 v76, v72
	v_permlane16_swap_b32_e32 v77, v73
	v_permlane16_swap_b32_e32 v78, v74
	v_permlane16_swap_b32_e32 v79, v75
	v_permlane16_swap_b32_e32 v68, v64
	v_permlane16_swap_b32_e32 v69, v65
	v_permlane16_swap_b32_e32 v70, v66
	v_permlane16_swap_b32_e32 v71, v67
	v_permlane16_swap_b32_e32 v60, v56
	v_permlane16_swap_b32_e32 v61, v57
	v_permlane16_swap_b32_e32 v62, v58
	v_permlane16_swap_b32_e32 v63, v59
	v_permlane16_swap_b32_e32 v52, v48
	v_permlane16_swap_b32_e32 v53, v49
	v_permlane16_swap_b32_e32 v54, v50
	v_permlane16_swap_b32_e32 v55, v51
	v_permlane16_swap_b32_e32 v44, v40
	v_permlane16_swap_b32_e32 v45, v41
	v_permlane16_swap_b32_e32 v46, v42
	v_permlane16_swap_b32_e32 v47, v43
	v_permlane16_swap_b32_e32 v36, v32
	v_permlane16_swap_b32_e32 v37, v33
	v_permlane16_swap_b32_e32 v38, v34
	v_permlane16_swap_b32_e32 v39, v35
	v_permlane16_swap_b32_e32 v28, v24
	v_permlane16_swap_b32_e32 v29, v25
	v_permlane16_swap_b32_e32 v30, v26
	v_permlane16_swap_b32_e32 v31, v27
	v_permlane16_swap_b32_e32 v20, v16
	v_permlane16_swap_b32_e32 v21, v17
	v_permlane16_swap_b32_e32 v22, v18
	v_permlane16_swap_b32_e32 v23, v19
	v_permlane16_swap_b32_e32 v12, v8
	v_permlane16_swap_b32_e32 v13, v9
	v_permlane16_swap_b32_e32 v14, v10
	v_permlane16_swap_b32_e32 v15, v11
	v_permlane16_swap_b32_e32 v4, v0
	v_permlane16_swap_b32_e32 v5, v1
	v_permlane16_swap_b32_e32 v6, v2
	v_permlane16_swap_b32_e32 v7, v3
	s_waitcnt vmcnt(14)
	ds_bpermute_b32 v140, v253, v140
	ds_bpermute_b32 v141, v253, v141
	ds_bpermute_b32 v142, v253, v142
	ds_bpermute_b32 v143, v253, v143
	ds_bpermute_b32 v154, v253, v154
	ds_bpermute_b32 v155, v253, v155
	ds_bpermute_b32 v156, v253, v156
	ds_bpermute_b32 v157, v253, v157
	s_waitcnt lgkmcnt(0)
	v_lshlrev_b32_e32 v246, 16, v140
	v_and_b32_e32 v247, 0xffff0000, v140
	v_fma_f32 v124, v124, 0.5, v246
	v_fma_f32 v125, v125, 0.5, v247
	v_mul_f32_e32 v248, v124, v124
	v_fmac_f32_e32 v248, v125, v125
	v_cvt_pk_bf16_f32 v140, v124, v125
	v_lshlrev_b32_e32 v246, 16, v141
	v_and_b32_e32 v247, 0xffff0000, v141
	v_fma_f32 v126, v126, 0.5, v246
	v_fma_f32 v127, v127, 0.5, v247
	v_fmac_f32_e32 v248, v126, v126
	v_fmac_f32_e32 v248, v127, v127
	v_cvt_pk_bf16_f32 v141, v126, v127
	v_lshlrev_b32_e32 v246, 16, v142
	v_and_b32_e32 v247, 0xffff0000, v142
	v_fma_f32 v120, v120, 0.5, v246
	v_fma_f32 v121, v121, 0.5, v247
	v_fmac_f32_e32 v248, v120, v120
	v_fmac_f32_e32 v248, v121, v121
	v_cvt_pk_bf16_f32 v142, v120, v121
	v_lshlrev_b32_e32 v246, 16, v143
	v_and_b32_e32 v247, 0xffff0000, v143
	v_fma_f32 v122, v122, 0.5, v246
	v_fma_f32 v123, v123, 0.5, v247
	v_fmac_f32_e32 v248, v122, v122
	v_fmac_f32_e32 v248, v123, v123
	v_cvt_pk_bf16_f32 v143, v122, v123
	ds_bpermute_b32 v250, v252, v236
	ds_bpermute_b32 v251, v252, v237
	ds_bpermute_b32 v140, v252, v140
	ds_bpermute_b32 v141, v252, v141
	ds_bpermute_b32 v142, v252, v142
	ds_bpermute_b32 v143, v252, v143
	s_waitcnt lgkmcnt(0)
	global_store_dwordx4 v[250:251], v[140:143], off
	v_lshlrev_b32_e32 v246, 16, v154
	v_and_b32_e32 v247, 0xffff0000, v154
	v_fma_f32 v116, v116, 0.5, v246
	v_fma_f32 v117, v117, 0.5, v247
	v_fmac_f32_e32 v248, v116, v116
	v_fmac_f32_e32 v248, v117, v117
	v_cvt_pk_bf16_f32 v154, v116, v117
	v_lshlrev_b32_e32 v246, 16, v155
	v_and_b32_e32 v247, 0xffff0000, v155
	v_fma_f32 v118, v118, 0.5, v246
	v_fma_f32 v119, v119, 0.5, v247
	v_fmac_f32_e32 v248, v118, v118
	v_fmac_f32_e32 v248, v119, v119
	v_cvt_pk_bf16_f32 v155, v118, v119
	v_lshlrev_b32_e32 v246, 16, v156
	v_and_b32_e32 v247, 0xffff0000, v156
	v_fma_f32 v112, v112, 0.5, v246
	v_fma_f32 v113, v113, 0.5, v247
	v_fmac_f32_e32 v248, v112, v112
	v_fmac_f32_e32 v248, v113, v113
	v_cvt_pk_bf16_f32 v156, v112, v113
	v_lshlrev_b32_e32 v246, 16, v157
	v_and_b32_e32 v247, 0xffff0000, v157
	v_fma_f32 v114, v114, 0.5, v246
	v_fma_f32 v115, v115, 0.5, v247
	v_fmac_f32_e32 v248, v114, v114
	v_fmac_f32_e32 v248, v115, v115
	v_cvt_pk_bf16_f32 v157, v114, v115
	ds_bpermute_b32 v154, v252, v154
	ds_bpermute_b32 v155, v252, v155
	ds_bpermute_b32 v156, v252, v156
	ds_bpermute_b32 v157, v252, v157
	s_waitcnt lgkmcnt(0)
	global_store_dwordx4 v[250:251], v[154:157], off offset:256
	s_waitcnt vmcnt(14)
	ds_bpermute_b32 v158, v253, v158
	ds_bpermute_b32 v159, v253, v159
	ds_bpermute_b32 v160, v253, v160
	ds_bpermute_b32 v161, v253, v161
	ds_bpermute_b32 v162, v253, v162
	ds_bpermute_b32 v163, v253, v163
	ds_bpermute_b32 v164, v253, v164
	ds_bpermute_b32 v165, v253, v165
	s_waitcnt lgkmcnt(0)
	s_mov_b32 s100, 0x10000
	v_lshl_add_u64 v[238:239], v[236:237], 0, s[100:101]
	v_lshlrev_b32_e32 v246, 16, v158
	v_and_b32_e32 v247, 0xffff0000, v158
	v_fma_f32 v108, v108, 0.5, v246
	v_fma_f32 v109, v109, 0.5, v247
	v_mul_f32_e32 v124, v108, v108
	v_fmac_f32_e32 v124, v109, v109
	v_cvt_pk_bf16_f32 v158, v108, v109
	v_lshlrev_b32_e32 v246, 16, v159
	v_and_b32_e32 v247, 0xffff0000, v159
	v_fma_f32 v110, v110, 0.5, v246
	v_fma_f32 v111, v111, 0.5, v247
	v_fmac_f32_e32 v124, v110, v110
	v_fmac_f32_e32 v124, v111, v111
	v_cvt_pk_bf16_f32 v159, v110, v111
	v_lshlrev_b32_e32 v246, 16, v160
	v_and_b32_e32 v247, 0xffff0000, v160
	v_fma_f32 v104, v104, 0.5, v246
	v_fma_f32 v105, v105, 0.5, v247
	v_fmac_f32_e32 v124, v104, v104
	v_fmac_f32_e32 v124, v105, v105
	v_cvt_pk_bf16_f32 v160, v104, v105
	v_lshlrev_b32_e32 v246, 16, v161
	v_and_b32_e32 v247, 0xffff0000, v161
	v_fma_f32 v106, v106, 0.5, v246
	v_fma_f32 v107, v107, 0.5, v247
	v_fmac_f32_e32 v124, v106, v106
	v_fmac_f32_e32 v124, v107, v107
	v_cvt_pk_bf16_f32 v161, v106, v107
	ds_bpermute_b32 v250, v252, v238
	ds_bpermute_b32 v251, v252, v239
	ds_bpermute_b32 v158, v252, v158
	ds_bpermute_b32 v159, v252, v159
	ds_bpermute_b32 v160, v252, v160
	ds_bpermute_b32 v161, v252, v161
	s_waitcnt lgkmcnt(0)
	global_store_dwordx4 v[250:251], v[158:161], off
	v_lshlrev_b32_e32 v246, 16, v162
	v_and_b32_e32 v247, 0xffff0000, v162
	v_fma_f32 v100, v100, 0.5, v246
	v_fma_f32 v101, v101, 0.5, v247
	v_fmac_f32_e32 v124, v100, v100
	v_fmac_f32_e32 v124, v101, v101
	v_cvt_pk_bf16_f32 v162, v100, v101
	v_lshlrev_b32_e32 v246, 16, v163
	v_and_b32_e32 v247, 0xffff0000, v163
	v_fma_f32 v102, v102, 0.5, v246
	v_fma_f32 v103, v103, 0.5, v247
	v_fmac_f32_e32 v124, v102, v102
	v_fmac_f32_e32 v124, v103, v103
	v_cvt_pk_bf16_f32 v163, v102, v103
	v_lshlrev_b32_e32 v246, 16, v164
	v_and_b32_e32 v247, 0xffff0000, v164
	v_fma_f32 v96, v96, 0.5, v246
	v_fma_f32 v97, v97, 0.5, v247
	v_fmac_f32_e32 v124, v96, v96
	v_fmac_f32_e32 v124, v97, v97
	v_cvt_pk_bf16_f32 v164, v96, v97
	v_lshlrev_b32_e32 v246, 16, v165
	v_and_b32_e32 v247, 0xffff0000, v165
	v_fma_f32 v98, v98, 0.5, v246
	v_fma_f32 v99, v99, 0.5, v247
	v_fmac_f32_e32 v124, v98, v98
	v_fmac_f32_e32 v124, v99, v99
	v_cvt_pk_bf16_f32 v165, v98, v99
	ds_bpermute_b32 v162, v252, v162
	ds_bpermute_b32 v163, v252, v163
	ds_bpermute_b32 v164, v252, v164
	ds_bpermute_b32 v165, v252, v165
	s_waitcnt lgkmcnt(0)
	global_store_dwordx4 v[250:251], v[162:165], off offset:256
	s_waitcnt vmcnt(14)
	ds_bpermute_b32 v166, v253, v166
	ds_bpermute_b32 v167, v253, v167
	ds_bpermute_b32 v168, v253, v168
	ds_bpermute_b32 v169, v253, v169
	ds_bpermute_b32 v170, v253, v170
	ds_bpermute_b32 v171, v253, v171
	ds_bpermute_b32 v172, v253, v172
	ds_bpermute_b32 v173, v253, v173
	s_waitcnt lgkmcnt(0)
	s_mov_b32 s100, 0x20000
	v_lshl_add_u64 v[238:239], v[236:237], 0, s[100:101]
	v_lshlrev_b32_e32 v246, 16, v166
	v_and_b32_e32 v247, 0xffff0000, v166
	v_fma_f32 v92, v92, 0.5, v246
	v_fma_f32 v93, v93, 0.5, v247
	v_mul_f32_e32 v108, v92, v92
	v_fmac_f32_e32 v108, v93, v93
	v_cvt_pk_bf16_f32 v166, v92, v93
	v_lshlrev_b32_e32 v246, 16, v167
	v_and_b32_e32 v247, 0xffff0000, v167
	v_fma_f32 v94, v94, 0.5, v246
	v_fma_f32 v95, v95, 0.5, v247
	v_fmac_f32_e32 v108, v94, v94
	v_fmac_f32_e32 v108, v95, v95
	v_cvt_pk_bf16_f32 v167, v94, v95
	v_lshlrev_b32_e32 v246, 16, v168
	v_and_b32_e32 v247, 0xffff0000, v168
	v_fma_f32 v88, v88, 0.5, v246
	v_fma_f32 v89, v89, 0.5, v247
	v_fmac_f32_e32 v108, v88, v88
	v_fmac_f32_e32 v108, v89, v89
	v_cvt_pk_bf16_f32 v168, v88, v89
	v_lshlrev_b32_e32 v246, 16, v169
	v_and_b32_e32 v247, 0xffff0000, v169
	v_fma_f32 v90, v90, 0.5, v246
	v_fma_f32 v91, v91, 0.5, v247
	v_fmac_f32_e32 v108, v90, v90
	v_fmac_f32_e32 v108, v91, v91
	v_cvt_pk_bf16_f32 v169, v90, v91
	ds_bpermute_b32 v250, v252, v238
	ds_bpermute_b32 v251, v252, v239
	ds_bpermute_b32 v166, v252, v166
	ds_bpermute_b32 v167, v252, v167
	ds_bpermute_b32 v168, v252, v168
	ds_bpermute_b32 v169, v252, v169
	s_waitcnt lgkmcnt(0)
	global_store_dwordx4 v[250:251], v[166:169], off
	v_lshlrev_b32_e32 v246, 16, v170
	v_and_b32_e32 v247, 0xffff0000, v170
	v_fma_f32 v84, v84, 0.5, v246
	v_fma_f32 v85, v85, 0.5, v247
	v_fmac_f32_e32 v108, v84, v84
	v_fmac_f32_e32 v108, v85, v85
	v_cvt_pk_bf16_f32 v170, v84, v85
	v_lshlrev_b32_e32 v246, 16, v171
	v_and_b32_e32 v247, 0xffff0000, v171
	v_fma_f32 v86, v86, 0.5, v246
	v_fma_f32 v87, v87, 0.5, v247
	v_fmac_f32_e32 v108, v86, v86
	v_fmac_f32_e32 v108, v87, v87
	v_cvt_pk_bf16_f32 v171, v86, v87
	v_lshlrev_b32_e32 v246, 16, v172
	v_and_b32_e32 v247, 0xffff0000, v172
	v_fma_f32 v80, v80, 0.5, v246
	v_fma_f32 v81, v81, 0.5, v247
	v_fmac_f32_e32 v108, v80, v80
	v_fmac_f32_e32 v108, v81, v81
	v_cvt_pk_bf16_f32 v172, v80, v81
	v_lshlrev_b32_e32 v246, 16, v173
	v_and_b32_e32 v247, 0xffff0000, v173
	v_fma_f32 v82, v82, 0.5, v246
	v_fma_f32 v83, v83, 0.5, v247
	v_fmac_f32_e32 v108, v82, v82
	v_fmac_f32_e32 v108, v83, v83
	v_cvt_pk_bf16_f32 v173, v82, v83
	ds_bpermute_b32 v170, v252, v170
	ds_bpermute_b32 v171, v252, v171
	ds_bpermute_b32 v172, v252, v172
	ds_bpermute_b32 v173, v252, v173
	s_waitcnt lgkmcnt(0)
	global_store_dwordx4 v[250:251], v[170:173], off offset:256
	s_waitcnt vmcnt(14)
	ds_bpermute_b32 v174, v253, v174
	ds_bpermute_b32 v175, v253, v175
	ds_bpermute_b32 v176, v253, v176
	ds_bpermute_b32 v177, v253, v177
	ds_bpermute_b32 v178, v253, v178
	ds_bpermute_b32 v179, v253, v179
	ds_bpermute_b32 v180, v253, v180
	ds_bpermute_b32 v181, v253, v181
	s_waitcnt lgkmcnt(0)
	s_mov_b32 s100, 0x30000
	v_lshl_add_u64 v[238:239], v[236:237], 0, s[100:101]
	v_lshlrev_b32_e32 v246, 16, v174
	v_and_b32_e32 v247, 0xffff0000, v174
	v_fma_f32 v76, v76, 0.5, v246
	v_fma_f32 v77, v77, 0.5, v247
	v_mul_f32_e32 v92, v76, v76
	v_fmac_f32_e32 v92, v77, v77
	v_cvt_pk_bf16_f32 v174, v76, v77
	v_lshlrev_b32_e32 v246, 16, v175
	v_and_b32_e32 v247, 0xffff0000, v175
	v_fma_f32 v78, v78, 0.5, v246
	v_fma_f32 v79, v79, 0.5, v247
	v_fmac_f32_e32 v92, v78, v78
	v_fmac_f32_e32 v92, v79, v79
	v_cvt_pk_bf16_f32 v175, v78, v79
	v_lshlrev_b32_e32 v246, 16, v176
	v_and_b32_e32 v247, 0xffff0000, v176
	v_fma_f32 v72, v72, 0.5, v246
	v_fma_f32 v73, v73, 0.5, v247
	v_fmac_f32_e32 v92, v72, v72
	v_fmac_f32_e32 v92, v73, v73
	v_cvt_pk_bf16_f32 v176, v72, v73
	v_lshlrev_b32_e32 v246, 16, v177
	v_and_b32_e32 v247, 0xffff0000, v177
	v_fma_f32 v74, v74, 0.5, v246
	v_fma_f32 v75, v75, 0.5, v247
	v_fmac_f32_e32 v92, v74, v74
	v_fmac_f32_e32 v92, v75, v75
	v_cvt_pk_bf16_f32 v177, v74, v75
	ds_bpermute_b32 v250, v252, v238
	ds_bpermute_b32 v251, v252, v239
	ds_bpermute_b32 v174, v252, v174
	ds_bpermute_b32 v175, v252, v175
	ds_bpermute_b32 v176, v252, v176
	ds_bpermute_b32 v177, v252, v177
	s_waitcnt lgkmcnt(0)
	global_store_dwordx4 v[250:251], v[174:177], off
	v_lshlrev_b32_e32 v246, 16, v178
	v_and_b32_e32 v247, 0xffff0000, v178
	v_fma_f32 v68, v68, 0.5, v246
	v_fma_f32 v69, v69, 0.5, v247
	v_fmac_f32_e32 v92, v68, v68
	v_fmac_f32_e32 v92, v69, v69
	v_cvt_pk_bf16_f32 v178, v68, v69
	v_lshlrev_b32_e32 v246, 16, v179
	v_and_b32_e32 v247, 0xffff0000, v179
	v_fma_f32 v70, v70, 0.5, v246
	v_fma_f32 v71, v71, 0.5, v247
	v_fmac_f32_e32 v92, v70, v70
	v_fmac_f32_e32 v92, v71, v71
	v_cvt_pk_bf16_f32 v179, v70, v71
	v_lshlrev_b32_e32 v246, 16, v180
	v_and_b32_e32 v247, 0xffff0000, v180
	v_fma_f32 v64, v64, 0.5, v246
	v_fma_f32 v65, v65, 0.5, v247
	v_fmac_f32_e32 v92, v64, v64
	v_fmac_f32_e32 v92, v65, v65
	v_cvt_pk_bf16_f32 v180, v64, v65
	v_lshlrev_b32_e32 v246, 16, v181
	v_and_b32_e32 v247, 0xffff0000, v181
	v_fma_f32 v66, v66, 0.5, v246
	v_fma_f32 v67, v67, 0.5, v247
	v_fmac_f32_e32 v92, v66, v66
	v_fmac_f32_e32 v92, v67, v67
	v_cvt_pk_bf16_f32 v181, v66, v67
	ds_bpermute_b32 v178, v252, v178
	ds_bpermute_b32 v179, v252, v179
	ds_bpermute_b32 v180, v252, v180
	ds_bpermute_b32 v181, v252, v181
	s_waitcnt lgkmcnt(0)
	global_store_dwordx4 v[250:251], v[178:181], off offset:256
	s_waitcnt vmcnt(14)
	ds_bpermute_b32 v184, v253, v184
	ds_bpermute_b32 v185, v253, v185
	ds_bpermute_b32 v186, v253, v186
	ds_bpermute_b32 v187, v253, v187
	ds_bpermute_b32 v188, v253, v188
	ds_bpermute_b32 v189, v253, v189
	ds_bpermute_b32 v190, v253, v190
	ds_bpermute_b32 v191, v253, v191
	s_waitcnt lgkmcnt(0)
	s_mov_b32 s100, 0x80000
	v_lshl_add_u64 v[238:239], v[236:237], 0, s[100:101]
	v_lshlrev_b32_e32 v246, 16, v184
	v_and_b32_e32 v247, 0xffff0000, v184
	v_fma_f32 v60, v60, 0.5, v246
	v_fma_f32 v61, v61, 0.5, v247
	v_mul_f32_e32 v76, v60, v60
	v_fmac_f32_e32 v76, v61, v61
	v_cvt_pk_bf16_f32 v184, v60, v61
	v_lshlrev_b32_e32 v246, 16, v185
	v_and_b32_e32 v247, 0xffff0000, v185
	v_fma_f32 v62, v62, 0.5, v246
	v_fma_f32 v63, v63, 0.5, v247
	v_fmac_f32_e32 v76, v62, v62
	v_fmac_f32_e32 v76, v63, v63
	v_cvt_pk_bf16_f32 v185, v62, v63
	v_lshlrev_b32_e32 v246, 16, v186
	v_and_b32_e32 v247, 0xffff0000, v186
	v_fma_f32 v56, v56, 0.5, v246
	v_fma_f32 v57, v57, 0.5, v247
	v_fmac_f32_e32 v76, v56, v56
	v_fmac_f32_e32 v76, v57, v57
	v_cvt_pk_bf16_f32 v186, v56, v57
	v_lshlrev_b32_e32 v246, 16, v187
	v_and_b32_e32 v247, 0xffff0000, v187
	v_fma_f32 v58, v58, 0.5, v246
	v_fma_f32 v59, v59, 0.5, v247
	v_fmac_f32_e32 v76, v58, v58
	v_fmac_f32_e32 v76, v59, v59
	v_cvt_pk_bf16_f32 v187, v58, v59
	ds_bpermute_b32 v250, v252, v238
	ds_bpermute_b32 v251, v252, v239
	ds_bpermute_b32 v184, v252, v184
	ds_bpermute_b32 v185, v252, v185
	ds_bpermute_b32 v186, v252, v186
	ds_bpermute_b32 v187, v252, v187
	s_waitcnt lgkmcnt(0)
	global_store_dwordx4 v[250:251], v[184:187], off
	v_lshlrev_b32_e32 v246, 16, v188
	v_and_b32_e32 v247, 0xffff0000, v188
	v_fma_f32 v52, v52, 0.5, v246
	v_fma_f32 v53, v53, 0.5, v247
	v_fmac_f32_e32 v76, v52, v52
	v_fmac_f32_e32 v76, v53, v53
	v_cvt_pk_bf16_f32 v188, v52, v53
	v_lshlrev_b32_e32 v246, 16, v189
	v_and_b32_e32 v247, 0xffff0000, v189
	v_fma_f32 v54, v54, 0.5, v246
	v_fma_f32 v55, v55, 0.5, v247
	v_fmac_f32_e32 v76, v54, v54
	v_fmac_f32_e32 v76, v55, v55
	v_cvt_pk_bf16_f32 v189, v54, v55
	v_lshlrev_b32_e32 v246, 16, v190
	v_and_b32_e32 v247, 0xffff0000, v190
	v_fma_f32 v48, v48, 0.5, v246
	v_fma_f32 v49, v49, 0.5, v247
	v_fmac_f32_e32 v76, v48, v48
	v_fmac_f32_e32 v76, v49, v49
	v_cvt_pk_bf16_f32 v190, v48, v49
	v_lshlrev_b32_e32 v246, 16, v191
	v_and_b32_e32 v247, 0xffff0000, v191
	v_fma_f32 v50, v50, 0.5, v246
	v_fma_f32 v51, v51, 0.5, v247
	v_fmac_f32_e32 v76, v50, v50
	v_fmac_f32_e32 v76, v51, v51
	v_cvt_pk_bf16_f32 v191, v50, v51
	ds_bpermute_b32 v188, v252, v188
	ds_bpermute_b32 v189, v252, v189
	ds_bpermute_b32 v190, v252, v190
	ds_bpermute_b32 v191, v252, v191
	s_waitcnt lgkmcnt(0)
	global_store_dwordx4 v[250:251], v[188:191], off offset:256
	s_waitcnt vmcnt(14)
	ds_bpermute_b32 v192, v253, v192
	ds_bpermute_b32 v193, v253, v193
	ds_bpermute_b32 v194, v253, v194
	ds_bpermute_b32 v195, v253, v195
	ds_bpermute_b32 v196, v253, v196
	ds_bpermute_b32 v197, v253, v197
	ds_bpermute_b32 v198, v253, v198
	ds_bpermute_b32 v199, v253, v199
	s_waitcnt lgkmcnt(0)
	s_mov_b32 s100, 0x90000
	v_lshl_add_u64 v[238:239], v[236:237], 0, s[100:101]
	v_lshlrev_b32_e32 v246, 16, v192
	v_and_b32_e32 v247, 0xffff0000, v192
	v_fma_f32 v44, v44, 0.5, v246
	v_fma_f32 v45, v45, 0.5, v247
	v_mul_f32_e32 v60, v44, v44
	v_fmac_f32_e32 v60, v45, v45
	v_cvt_pk_bf16_f32 v192, v44, v45
	v_lshlrev_b32_e32 v246, 16, v193
	v_and_b32_e32 v247, 0xffff0000, v193
	v_fma_f32 v46, v46, 0.5, v246
	v_fma_f32 v47, v47, 0.5, v247
	v_fmac_f32_e32 v60, v46, v46
	v_fmac_f32_e32 v60, v47, v47
	v_cvt_pk_bf16_f32 v193, v46, v47
	v_lshlrev_b32_e32 v246, 16, v194
	v_and_b32_e32 v247, 0xffff0000, v194
	v_fma_f32 v40, v40, 0.5, v246
	v_fma_f32 v41, v41, 0.5, v247
	v_fmac_f32_e32 v60, v40, v40
	v_fmac_f32_e32 v60, v41, v41
	v_cvt_pk_bf16_f32 v194, v40, v41
	v_lshlrev_b32_e32 v246, 16, v195
	v_and_b32_e32 v247, 0xffff0000, v195
	v_fma_f32 v42, v42, 0.5, v246
	v_fma_f32 v43, v43, 0.5, v247
	v_fmac_f32_e32 v60, v42, v42
	v_fmac_f32_e32 v60, v43, v43
	v_cvt_pk_bf16_f32 v195, v42, v43
	ds_bpermute_b32 v250, v252, v238
	ds_bpermute_b32 v251, v252, v239
	ds_bpermute_b32 v192, v252, v192
	ds_bpermute_b32 v193, v252, v193
	ds_bpermute_b32 v194, v252, v194
	ds_bpermute_b32 v195, v252, v195
	s_waitcnt lgkmcnt(0)
	global_store_dwordx4 v[250:251], v[192:195], off
	v_lshlrev_b32_e32 v246, 16, v196
	v_and_b32_e32 v247, 0xffff0000, v196
	v_fma_f32 v36, v36, 0.5, v246
	v_fma_f32 v37, v37, 0.5, v247
	v_fmac_f32_e32 v60, v36, v36
	v_fmac_f32_e32 v60, v37, v37
	v_cvt_pk_bf16_f32 v196, v36, v37
	v_lshlrev_b32_e32 v246, 16, v197
	v_and_b32_e32 v247, 0xffff0000, v197
	v_fma_f32 v38, v38, 0.5, v246
	v_fma_f32 v39, v39, 0.5, v247
	v_fmac_f32_e32 v60, v38, v38
	v_fmac_f32_e32 v60, v39, v39
	v_cvt_pk_bf16_f32 v197, v38, v39
	v_lshlrev_b32_e32 v246, 16, v198
	v_and_b32_e32 v247, 0xffff0000, v198
	v_fma_f32 v32, v32, 0.5, v246
	v_fma_f32 v33, v33, 0.5, v247
	v_fmac_f32_e32 v60, v32, v32
	v_fmac_f32_e32 v60, v33, v33
	v_cvt_pk_bf16_f32 v198, v32, v33
	v_lshlrev_b32_e32 v246, 16, v199
	v_and_b32_e32 v247, 0xffff0000, v199
	v_fma_f32 v34, v34, 0.5, v246
	v_fma_f32 v35, v35, 0.5, v247
	v_fmac_f32_e32 v60, v34, v34
	v_fmac_f32_e32 v60, v35, v35
	v_cvt_pk_bf16_f32 v199, v34, v35
	ds_bpermute_b32 v196, v252, v196
	ds_bpermute_b32 v197, v252, v197
	ds_bpermute_b32 v198, v252, v198
	ds_bpermute_b32 v199, v252, v199
	s_waitcnt lgkmcnt(0)
	global_store_dwordx4 v[250:251], v[196:199], off offset:256
	s_waitcnt vmcnt(14)
	ds_bpermute_b32 v200, v253, v200
	ds_bpermute_b32 v201, v253, v201
	ds_bpermute_b32 v202, v253, v202
	ds_bpermute_b32 v203, v253, v203
	ds_bpermute_b32 v204, v253, v204
	ds_bpermute_b32 v205, v253, v205
	ds_bpermute_b32 v206, v253, v206
	ds_bpermute_b32 v207, v253, v207
	s_waitcnt lgkmcnt(0)
	s_mov_b32 s100, 0xa0000
	v_lshl_add_u64 v[238:239], v[236:237], 0, s[100:101]
	v_lshlrev_b32_e32 v246, 16, v200
	v_and_b32_e32 v247, 0xffff0000, v200
	v_fma_f32 v28, v28, 0.5, v246
	v_fma_f32 v29, v29, 0.5, v247
	v_mul_f32_e32 v44, v28, v28
	v_fmac_f32_e32 v44, v29, v29
	v_cvt_pk_bf16_f32 v200, v28, v29
	v_lshlrev_b32_e32 v246, 16, v201
	v_and_b32_e32 v247, 0xffff0000, v201
	v_fma_f32 v30, v30, 0.5, v246
	v_fma_f32 v31, v31, 0.5, v247
	v_fmac_f32_e32 v44, v30, v30
	v_fmac_f32_e32 v44, v31, v31
	v_cvt_pk_bf16_f32 v201, v30, v31
	v_lshlrev_b32_e32 v246, 16, v202
	v_and_b32_e32 v247, 0xffff0000, v202
	v_fma_f32 v24, v24, 0.5, v246
	v_fma_f32 v25, v25, 0.5, v247
	v_fmac_f32_e32 v44, v24, v24
	v_fmac_f32_e32 v44, v25, v25
	v_cvt_pk_bf16_f32 v202, v24, v25
	v_lshlrev_b32_e32 v246, 16, v203
	v_and_b32_e32 v247, 0xffff0000, v203
	v_fma_f32 v26, v26, 0.5, v246
	v_fma_f32 v27, v27, 0.5, v247
	v_fmac_f32_e32 v44, v26, v26
	v_fmac_f32_e32 v44, v27, v27
	v_cvt_pk_bf16_f32 v203, v26, v27
	ds_bpermute_b32 v250, v252, v238
	ds_bpermute_b32 v251, v252, v239
	ds_bpermute_b32 v200, v252, v200
	ds_bpermute_b32 v201, v252, v201
	ds_bpermute_b32 v202, v252, v202
	ds_bpermute_b32 v203, v252, v203
	s_waitcnt lgkmcnt(0)
	global_store_dwordx4 v[250:251], v[200:203], off
	v_lshlrev_b32_e32 v246, 16, v204
	v_and_b32_e32 v247, 0xffff0000, v204
	v_fma_f32 v20, v20, 0.5, v246
	v_fma_f32 v21, v21, 0.5, v247
	v_fmac_f32_e32 v44, v20, v20
	v_fmac_f32_e32 v44, v21, v21
	v_cvt_pk_bf16_f32 v204, v20, v21
	v_lshlrev_b32_e32 v246, 16, v205
	v_and_b32_e32 v247, 0xffff0000, v205
	v_fma_f32 v22, v22, 0.5, v246
	v_fma_f32 v23, v23, 0.5, v247
	v_fmac_f32_e32 v44, v22, v22
	v_fmac_f32_e32 v44, v23, v23
	v_cvt_pk_bf16_f32 v205, v22, v23
	v_lshlrev_b32_e32 v246, 16, v206
	v_and_b32_e32 v247, 0xffff0000, v206
	v_fma_f32 v16, v16, 0.5, v246
	v_fma_f32 v17, v17, 0.5, v247
	v_fmac_f32_e32 v44, v16, v16
	v_fmac_f32_e32 v44, v17, v17
	v_cvt_pk_bf16_f32 v206, v16, v17
	v_lshlrev_b32_e32 v246, 16, v207
	v_and_b32_e32 v247, 0xffff0000, v207
	v_fma_f32 v18, v18, 0.5, v246
	v_fma_f32 v19, v19, 0.5, v247
	v_fmac_f32_e32 v44, v18, v18
	v_fmac_f32_e32 v44, v19, v19
	v_cvt_pk_bf16_f32 v207, v18, v19
	ds_bpermute_b32 v204, v252, v204
	ds_bpermute_b32 v205, v252, v205
	ds_bpermute_b32 v206, v252, v206
	ds_bpermute_b32 v207, v252, v207
	s_waitcnt lgkmcnt(0)
	global_store_dwordx4 v[250:251], v[204:207], off offset:256
	s_waitcnt vmcnt(14)
	ds_bpermute_b32 v208, v253, v208
	ds_bpermute_b32 v209, v253, v209
	ds_bpermute_b32 v210, v253, v210
	ds_bpermute_b32 v211, v253, v211
	ds_bpermute_b32 v212, v253, v212
	ds_bpermute_b32 v213, v253, v213
	ds_bpermute_b32 v214, v253, v214
	ds_bpermute_b32 v215, v253, v215
	s_waitcnt lgkmcnt(0)
	s_mov_b32 s100, 0xb0000
	v_lshl_add_u64 v[238:239], v[236:237], 0, s[100:101]
	v_lshlrev_b32_e32 v246, 16, v208
	v_and_b32_e32 v247, 0xffff0000, v208
	v_fma_f32 v12, v12, 0.5, v246
	v_fma_f32 v13, v13, 0.5, v247
	v_mul_f32_e32 v28, v12, v12
	v_fmac_f32_e32 v28, v13, v13
	v_cvt_pk_bf16_f32 v208, v12, v13
	v_lshlrev_b32_e32 v246, 16, v209
	v_and_b32_e32 v247, 0xffff0000, v209
	v_fma_f32 v14, v14, 0.5, v246
	v_fma_f32 v15, v15, 0.5, v247
	v_fmac_f32_e32 v28, v14, v14
	v_fmac_f32_e32 v28, v15, v15
	v_cvt_pk_bf16_f32 v209, v14, v15
	v_lshlrev_b32_e32 v246, 16, v210
	v_and_b32_e32 v247, 0xffff0000, v210
	v_fma_f32 v8, v8, 0.5, v246
	v_fma_f32 v9, v9, 0.5, v247
	v_fmac_f32_e32 v28, v8, v8
	v_fmac_f32_e32 v28, v9, v9
	v_cvt_pk_bf16_f32 v210, v8, v9
	v_lshlrev_b32_e32 v246, 16, v211
	v_and_b32_e32 v247, 0xffff0000, v211
	v_fma_f32 v10, v10, 0.5, v246
	v_fma_f32 v11, v11, 0.5, v247
	v_fmac_f32_e32 v28, v10, v10
	v_fmac_f32_e32 v28, v11, v11
	v_cvt_pk_bf16_f32 v211, v10, v11
	ds_bpermute_b32 v250, v252, v238
	ds_bpermute_b32 v251, v252, v239
	ds_bpermute_b32 v208, v252, v208
	ds_bpermute_b32 v209, v252, v209
	ds_bpermute_b32 v210, v252, v210
	ds_bpermute_b32 v211, v252, v211
	s_waitcnt lgkmcnt(0)
	global_store_dwordx4 v[250:251], v[208:211], off
	v_lshlrev_b32_e32 v246, 16, v212
	v_and_b32_e32 v247, 0xffff0000, v212
	v_fma_f32 v4, v4, 0.5, v246
	v_fma_f32 v5, v5, 0.5, v247
	v_fmac_f32_e32 v28, v4, v4
	v_fmac_f32_e32 v28, v5, v5
	v_cvt_pk_bf16_f32 v212, v4, v5
	v_lshlrev_b32_e32 v246, 16, v213
	v_and_b32_e32 v247, 0xffff0000, v213
	v_fma_f32 v6, v6, 0.5, v246
	v_fma_f32 v7, v7, 0.5, v247
	v_fmac_f32_e32 v28, v6, v6
	v_fmac_f32_e32 v28, v7, v7
	v_cvt_pk_bf16_f32 v213, v6, v7
	v_lshlrev_b32_e32 v246, 16, v214
	v_and_b32_e32 v247, 0xffff0000, v214
	v_fma_f32 v0, v0, 0.5, v246
	v_fma_f32 v1, v1, 0.5, v247
	v_fmac_f32_e32 v28, v0, v0
	v_fmac_f32_e32 v28, v1, v1
	v_cvt_pk_bf16_f32 v214, v0, v1
	v_lshlrev_b32_e32 v246, 16, v215
	v_and_b32_e32 v247, 0xffff0000, v215
	v_fma_f32 v2, v2, 0.5, v246
	v_fma_f32 v3, v3, 0.5, v247
	v_fmac_f32_e32 v28, v2, v2
	v_fmac_f32_e32 v28, v3, v3
	v_cvt_pk_bf16_f32 v215, v2, v3
	ds_bpermute_b32 v212, v252, v212
	ds_bpermute_b32 v213, v252, v213
	ds_bpermute_b32 v214, v252, v214
	ds_bpermute_b32 v215, v252, v215
	s_waitcnt lgkmcnt(0)
	global_store_dwordx4 v[250:251], v[212:215], off offset:256
	ds_bpermute_b32 v0, v244, v248
	ds_bpermute_b32 v1, v244, v124
	ds_bpermute_b32 v2, v244, v108
	ds_bpermute_b32 v3, v244, v92
	ds_bpermute_b32 v8, v244, v76
	ds_bpermute_b32 v9, v244, v60
	ds_bpermute_b32 v10, v244, v44
	ds_bpermute_b32 v11, v244, v28
	s_waitcnt lgkmcnt(7)
	v_add_f32_e32 v248, v248, v0
	s_waitcnt lgkmcnt(6)
	v_add_f32_e32 v124, v124, v1
	s_waitcnt lgkmcnt(5)
	v_add_f32_e32 v108, v108, v2
	s_waitcnt lgkmcnt(4)
	v_add_f32_e32 v92, v92, v3
	s_waitcnt lgkmcnt(3)
	v_add_f32_e32 v76, v76, v8
	s_waitcnt lgkmcnt(2)
	v_add_f32_e32 v60, v60, v9
	s_waitcnt lgkmcnt(1)
	v_add_f32_e32 v44, v44, v10
	s_waitcnt lgkmcnt(0)
	v_add_f32_e32 v28, v28, v11
	ds_bpermute_b32 v0, v245, v248
	ds_bpermute_b32 v1, v245, v124
	ds_bpermute_b32 v2, v245, v108
	ds_bpermute_b32 v3, v245, v92
	ds_bpermute_b32 v8, v245, v76
	ds_bpermute_b32 v9, v245, v60
	ds_bpermute_b32 v10, v245, v44
	ds_bpermute_b32 v11, v245, v28
	s_waitcnt lgkmcnt(7)
	v_add_f32_e32 v248, v248, v0
	s_waitcnt lgkmcnt(6)
	v_add_f32_e32 v124, v124, v1
	s_waitcnt lgkmcnt(5)
	v_add_f32_e32 v108, v108, v2
	s_waitcnt lgkmcnt(4)
	v_add_f32_e32 v92, v92, v3
	s_waitcnt lgkmcnt(3)
	v_add_f32_e32 v76, v76, v8
	s_waitcnt lgkmcnt(2)
	v_add_f32_e32 v60, v60, v9
	s_waitcnt lgkmcnt(1)
	v_add_f32_e32 v44, v44, v10
	s_waitcnt lgkmcnt(0)
	v_add_f32_e32 v28, v28, v11
	s_and_saveexec_b64 s[18:19], s[8:9]
	v_lshl_add_u64 v[236:237], v[240:241], 3, s[10:11]
	v_mul_f32_e32 v248, 0x4f800000, v248
	v_trunc_f32_e32 v248, v248
	v_mul_f32_e32 v0, 0x2f800000, v248
	v_floor_f32_e32 v0, v0
	v_fmac_f32_e32 v248, 0xcf800000, v0
	v_cvt_u32_f32_e32 v246, v248
	v_cvt_u32_f32_e32 v247, v0
	global_atomic_add_x2 v[236:237], v[246:247], off
	s_nop 1
	v_mul_f32_e32 v124, 0x4f800000, v124
	v_trunc_f32_e32 v124, v124
	v_mul_f32_e32 v1, 0x2f800000, v124
	v_floor_f32_e32 v1, v1
	v_fmac_f32_e32 v124, 0xcf800000, v1
	v_cvt_u32_f32_e32 v246, v124
	v_cvt_u32_f32_e32 v247, v1
	global_atomic_add_x2 v[236:237], v[246:247], off offset:128
	s_nop 1
	v_mul_f32_e32 v108, 0x4f800000, v108
	v_trunc_f32_e32 v108, v108
	v_mul_f32_e32 v2, 0x2f800000, v108
	v_floor_f32_e32 v2, v2
	v_fmac_f32_e32 v108, 0xcf800000, v2
	v_cvt_u32_f32_e32 v246, v108
	v_cvt_u32_f32_e32 v247, v2
	global_atomic_add_x2 v[236:237], v[246:247], off offset:256
	s_nop 1
	v_mul_f32_e32 v92, 0x4f800000, v92
	v_trunc_f32_e32 v92, v92
	v_mul_f32_e32 v3, 0x2f800000, v92
	v_floor_f32_e32 v3, v3
	v_fmac_f32_e32 v92, 0xcf800000, v3
	v_cvt_u32_f32_e32 v246, v92
	v_cvt_u32_f32_e32 v247, v3
	global_atomic_add_x2 v[236:237], v[246:247], off offset:384
	s_nop 1
	v_mul_f32_e32 v76, 0x4f800000, v76
	v_trunc_f32_e32 v76, v76
	v_mul_f32_e32 v8, 0x2f800000, v76
	v_floor_f32_e32 v8, v8
	v_fmac_f32_e32 v76, 0xcf800000, v8
	v_cvt_u32_f32_e32 v246, v76
	v_cvt_u32_f32_e32 v247, v8
	global_atomic_add_x2 v[236:237], v[246:247], off offset:1024
	s_nop 1
	v_mul_f32_e32 v60, 0x4f800000, v60
	v_trunc_f32_e32 v60, v60
	v_mul_f32_e32 v9, 0x2f800000, v60
	v_floor_f32_e32 v9, v9
	v_fmac_f32_e32 v60, 0xcf800000, v9
	v_cvt_u32_f32_e32 v246, v60
	v_cvt_u32_f32_e32 v247, v9
	global_atomic_add_x2 v[236:237], v[246:247], off offset:1152
	s_nop 1
	v_mul_f32_e32 v44, 0x4f800000, v44
	v_trunc_f32_e32 v44, v44
	v_mul_f32_e32 v10, 0x2f800000, v44
	v_floor_f32_e32 v10, v10
	v_fmac_f32_e32 v44, 0xcf800000, v10
	v_cvt_u32_f32_e32 v246, v44
	v_cvt_u32_f32_e32 v247, v10
	global_atomic_add_x2 v[236:237], v[246:247], off offset:1280
	s_nop 1
	v_mul_f32_e32 v28, 0x4f800000, v28
	v_trunc_f32_e32 v28, v28
	v_mul_f32_e32 v11, 0x2f800000, v28
	v_floor_f32_e32 v11, v11
	v_fmac_f32_e32 v28, 0xcf800000, v11
	v_cvt_u32_f32_e32 v246, v28
	v_cvt_u32_f32_e32 v247, v11
	global_atomic_add_x2 v[236:237], v[246:247], off offset:1408
	s_nop 1
